# residual-GEMM epilogues: per-row ssq partial reduction (shfl_xor 16/32) via v_permlane16/32_swap instead of ds_bpermute + lgkmcnt waits (80 sites)
# baseline (speedup 1.0000x reference)
; __device__ __forceinline__ unsigned cvt_pk_bf16(float lo, float hi) { unsigned r; asm volatile("v_cvt_pk_bf16_f32 %0, %1, %2" : "=v"(r) : "v"(lo), "v"(hi)); return r; }
;     __device__ __forceinline__ void operator()(const f32x4 (&acc)[2][2][4][2], const Unit& u, int wr, int wc, int fr, int fq) const {
;     ...
;         RESID_LOAD(0, 0);
; #pragma unroll
;         for (int g = 0; g < 4; ++g) {
;             if (g < 3) RESID_LOAD((g + 1) & 1, g + 1);
; #pragma unroll
;             for (int rr = 0; rr < 2; ++rr) {
;                 const int idx = 2 * g + rr, ai = idx >> 2, m = idx & 3;
;                 const int row = row0 + ai * HALF + m * 16;
;                 float* xr = X + (size_t)row * 1024 + col0; bf16_t* br = XB + (size_t)row * 1024 + col0;
;                 float ss = 0.f;
; #pragma unroll
;                 for (int bj = 0; bj < 2; ++bj) {
;                     f32x4* p = (f32x4*)(xr + bj * HALF);
;                     const f32x4 o0 = xv[g & 1][rr][bj][0] + acc[ai][bj][m][0] * scale, o1 = xv[g & 1][rr][bj][1] + acc[ai][bj][m][1] * scale;
;                     p[0] = o0; p[1] = o1;
;                     u32x4 w; w.x = cvt_pk_bf16(o0[0], o0[1]); w.y = cvt_pk_bf16(o0[2], o0[3]); w.z = cvt_pk_bf16(o1[0], o1[1]); w.w = cvt_pk_bf16(o1[2], o1[3]);
;                     *(u32x4*)(br + bj * HALF) = w;
;                     ss += (o0[0] * o0[0] + o0[1] * o0[1]) + (o0[2] * o0[2] + o0[3] * o0[3]) + (o1[0] * o1[0] + o1[1] * o1[1]) + (o1[2] * o1[2] + o1[3] * o1[3]);
;                 }
;                 ss += __shfl_xor(ss, 16); ss += __shfl_xor(ss, 32);
;                 if (fq == 0) ssq[(size_t)row * 16 + u.pn * 4 + wc] = ss;
;             }
.LBB0_3252:
	v_lshl_or_b32 v142, s63, 8, v243
	v_lshl_add_u32 v192, s64, 8, v1
	v_ashrrev_i32_e32 v143, 31, v142
	v_lshlrev_b64 v[250:251], 2, v[142:143]
	v_ashrrev_i32_e32 v193, 31, v192
	s_waitcnt lgkmcnt(0)
	v_lshl_add_u64 v[194:195], s[14:15], 0, v[250:251]
	v_lshlrev_b64 v[228:229], 12, v[192:193]
	v_lshl_add_u64 v[2:3], v[194:195], 0, v[228:229]
	global_load_dwordx4 v[62:65], v[2:3], off offset:16
	global_load_dwordx4 v[246:249], v[2:3], off
	global_load_dwordx4 v[50:53], v[2:3], off offset:528
	global_load_dwordx4 v[54:57], v[2:3], off offset:512
	v_or_b32_e32 v58, 16, v192
	v_ashrrev_i32_e32 v59, 31, v58
	v_or_b32_e32 v214, 32, v192
	v_or_b32_e32 v204, 48, v192
	v_lshlrev_b64 v[60:61], 12, v[58:59]
	v_ashrrev_i32_e32 v215, 31, v214
	v_ashrrev_i32_e32 v205, 31, v204
	v_lshl_add_u64 v[2:3], v[194:195], 0, v[60:61]
	v_lshlrev_b64 v[218:219], 12, v[214:215]
	v_lshlrev_b64 v[216:217], 12, v[204:205]
	global_load_dwordx4 v[42:45], v[2:3], off offset:16
	global_load_dwordx4 v[46:49], v[2:3], off
	global_load_dwordx4 v[34:37], v[2:3], off offset:528
	global_load_dwordx4 v[38:41], v[2:3], off offset:512
	v_lshl_add_u64 v[2:3], v[194:195], 0, v[218:219]
	v_lshl_add_u64 v[6:7], v[194:195], 0, v[216:217]
	global_load_dwordx4 v[26:29], v[2:3], off offset:16
	global_load_dwordx4 v[30:33], v[2:3], off
	global_load_dwordx4 v[14:17], v[2:3], off offset:528
	global_load_dwordx4 v[22:25], v[2:3], off offset:512
	global_load_dwordx4 v[10:13], v[6:7], off offset:16
	global_load_dwordx4 v[18:21], v[6:7], off
	s_nop 0
	global_load_dwordx4 v[2:5], v[6:7], off offset:528
	s_nop 0
	global_load_dwordx4 v[6:9], v[6:7], off offset:512
	v_lshl_add_u64 v[228:229], s[8:9], 0, v[228:229]
	v_lshl_add_u64 v[228:229], v[228:229], 0, v[250:251]
	v_lshlrev_b64 v[250:251], 11, v[192:193]
	v_lshl_add_u64 v[250:251], s[28:29], 0, v[250:251]
	v_lshl_add_u64 v[250:251], v[142:143], 1, v[250:251]
	s_lshl_b32 s38, s63, 2
	s_ashr_i32 s39, s38, 31
	s_waitcnt vmcnt(0)
	v_pk_add_f32 v[64:65], v[210:211], v[64:65]
	v_pk_add_f32 v[248:249], v[206:207], v[248:249]
	v_pk_add_f32 v[246:247], v[212:213], v[246:247]
	v_pk_add_f32 v[62:63], v[208:209], v[62:63]
	global_store_dwordx4 v[228:229], v[246:249], off
	global_store_dwordx4 v[228:229], v[62:65], off offset:16
	v_cvt_pk_bf16_f32 v206, v246, v247
	v_cvt_pk_bf16_f32 v207, v248, v249
	v_cvt_pk_bf16_f32 v208, v62, v63
	v_cvt_pk_bf16_f32 v209, v64, v65
	global_store_dwordx4 v[250:251], v[206:209], off
	s_nop 0
	v_mul_f32_e32 v63, v63, v63
	v_fmac_f32_e32 v63, v62, v62
	v_mul_f32_e32 v206, v247, v247
	v_mul_f32_e32 v207, v249, v249
	v_fmac_f32_e32 v206, v246, v246
	v_fmac_f32_e32 v207, v248, v248
	v_add_f32_e32 v206, v206, v207
	v_add_f32_e32 v62, v63, v206
	v_mul_f32_e32 v63, v65, v65
	v_fmac_f32_e32 v63, v64, v64
	v_pk_add_f32 v[56:57], v[202:203], v[56:57]
	v_pk_add_f32 v[54:55], v[200:201], v[54:55]
	v_add_f32_e32 v206, v63, v62
	v_pk_add_f32 v[52:53], v[198:199], v[52:53]
	v_pk_add_f32 v[50:51], v[196:197], v[50:51]
	global_store_dwordx4 v[228:229], v[54:57], off offset:512
	global_store_dwordx4 v[228:229], v[50:53], off offset:528
	v_cvt_pk_bf16_f32 v62, v54, v55
	v_cvt_pk_bf16_f32 v63, v56, v57
	v_cvt_pk_bf16_f32 v64, v50, v51
	v_cvt_pk_bf16_f32 v65, v52, v53
	s_nop 0
	v_mul_f32_e32 v55, v55, v55
	v_fmac_f32_e32 v55, v54, v54
	v_mul_f32_e32 v54, v57, v57
	v_fmac_f32_e32 v54, v56, v56
	v_mul_f32_e32 v51, v51, v51
	v_add_f32_e32 v54, v55, v54
	v_fmac_f32_e32 v51, v50, v50
	v_add_f32_e32 v50, v51, v54
	v_mul_f32_e32 v51, v53, v53
	v_fmac_f32_e32 v51, v52, v52
	v_add_f32_e32 v50, v51, v50
	v_add_f32_e32 v50, v206, v50
	v_mov_b32_e32 v51, v50
	s_nop 1
	v_permlane16_swap_b32 v51, v50
	global_store_dwordx4 v[250:251], v[62:65], off offset:256
	s_waitcnt lgkmcnt(0)
	v_add_f32_e32 v50, v50, v51
	v_mov_b32_e32 v51, v50
	s_nop 1
	v_permlane32_swap_b32 v51, v50
	s_and_saveexec_b64 s[40:41], s[4:5]
	s_cbranch_execz .LBB0_3254
	v_lshlrev_b64 v[52:53], 6, v[192:193]
	v_lshl_add_u64 v[52:53], s[10:11], 0, v[52:53]
	v_lshl_add_u64 v[52:53], s[38:39], 2, v[52:53]
	s_lshl_b32 s64, s50, 2
	s_mov_b32 s65, s68
	v_lshl_add_u64 v[52:53], v[52:53], 0, s[64:65]
	s_waitcnt lgkmcnt(0)
	v_add_f32_e32 v50, v50, v51
	global_store_dword v[52:53], v50, off
.LBB0_3254:
	s_or_b64 exec, exec, s[40:41]
	s_waitcnt lgkmcnt(0)
	v_lshl_add_u64 v[50:51], s[8:9], 0, v[60:61]
	v_lshl_add_u64 v[54:55], v[142:143], 2, v[50:51]
	v_lshlrev_b64 v[50:51], 11, v[58:59]
	v_lshl_add_u64 v[50:51], s[28:29], 0, v[50:51]
	v_pk_add_f32 v[48:49], v[190:191], v[48:49]
	v_pk_add_f32 v[46:47], v[188:189], v[46:47]
	v_lshl_add_u64 v[56:57], v[142:143], 1, v[50:51]
	v_pk_add_f32 v[44:45], v[186:187], v[44:45]
	v_pk_add_f32 v[42:43], v[184:185], v[42:43]
	global_store_dwordx4 v[54:55], v[46:49], off
	global_store_dwordx4 v[54:55], v[42:45], off offset:16
	v_cvt_pk_bf16_f32 v50, v46, v47
	v_cvt_pk_bf16_f32 v51, v48, v49
	v_cvt_pk_bf16_f32 v52, v42, v43
	v_pk_add_f32 v[40:41], v[182:183], v[40:41]
	v_mul_f32_e32 v47, v47, v47
	v_fmac_f32_e32 v47, v46, v46
	v_mul_f32_e32 v46, v49, v49
	v_fmac_f32_e32 v46, v48, v48
	v_mul_f32_e32 v43, v43, v43
	v_add_f32_e32 v46, v47, v46
	v_fmac_f32_e32 v43, v42, v42
	v_add_f32_e32 v42, v43, v46
	v_mul_f32_e32 v43, v45, v45
	v_fmac_f32_e32 v43, v44, v44
	v_pk_add_f32 v[38:39], v[180:181], v[38:39]
	v_add_f32_e32 v46, v43, v42
	v_pk_add_f32 v[42:43], v[176:177], v[34:35]
	v_mul_f32_e32 v34, v39, v39
	v_mul_f32_e32 v35, v41, v41
	v_fmac_f32_e32 v34, v38, v38
	v_fmac_f32_e32 v35, v40, v40
	v_add_f32_e32 v34, v34, v35
	v_mul_f32_e32 v35, v43, v43
	v_cvt_pk_bf16_f32 v53, v44, v45
	v_pk_add_f32 v[44:45], v[178:179], v[36:37]
	v_fmac_f32_e32 v35, v42, v42
	v_add_f32_e32 v34, v35, v34
	v_mul_f32_e32 v35, v45, v45
	v_fmac_f32_e32 v35, v44, v44
	v_add_f32_e32 v34, v35, v34
	v_add_f32_e32 v34, v46, v34
	v_mov_b32_e32 v35, v34
	s_nop 1
	v_permlane16_swap_b32 v35, v34
	global_store_dwordx4 v[56:57], v[50:53], off
	global_store_dwordx4 v[54:55], v[38:41], off offset:512
	global_store_dwordx4 v[54:55], v[42:45], off offset:528
	v_cvt_pk_bf16_f32 v36, v38, v39
	v_cvt_pk_bf16_f32 v37, v40, v41
	s_waitcnt lgkmcnt(0)
	v_add_f32_e32 v34, v34, v35
	v_mov_b32_e32 v35, v34
	s_nop 1
	v_permlane32_swap_b32 v35, v34
	v_cvt_pk_bf16_f32 v38, v42, v43
	v_cvt_pk_bf16_f32 v39, v44, v45
	global_store_dwordx4 v[56:57], v[36:39], off offset:256
	s_and_saveexec_b64 s[40:41], s[4:5]
	s_cbranch_execz .LBB0_3256
	v_lshlrev_b64 v[36:37], 6, v[58:59]
	v_lshl_add_u64 v[36:37], s[10:11], 0, v[36:37]
	v_lshl_add_u64 v[36:37], s[38:39], 2, v[36:37]
	s_lshl_b32 s64, s50, 2
	s_mov_b32 s65, s68
	v_lshl_add_u64 v[36:37], v[36:37], 0, s[64:65]
	s_waitcnt lgkmcnt(0)
	v_add_f32_e32 v34, v34, v35
	global_store_dword v[36:37], v34, off
; __device__ __forceinline__ unsigned cvt_pk_bf16(float lo, float hi) { unsigned r; asm volatile("v_cvt_pk_bf16_f32 %0, %1, %2" : "=v"(r) : "v"(lo), "v"(hi)); return r; }
;     __device__ __forceinline__ void operator()(const f32x4 (&acc)[2][2][4][2], const Unit& u, int wr, int wc, int fr, int fq) const {
;     ...
;         RESID_LOAD(0, 0);
; #pragma unroll
;         for (int g = 0; g < 4; ++g) {
;             if (g < 3) RESID_LOAD((g + 1) & 1, g + 1);
; #pragma unroll
;             for (int rr = 0; rr < 2; ++rr) {
;                 const int idx = 2 * g + rr, ai = idx >> 2, m = idx & 3;
;                 const int row = row0 + ai * HALF + m * 16;
;                 float* xr = X + (size_t)row * 1024 + col0; bf16_t* br = XB + (size_t)row * 1024 + col0;
;                 float ss = 0.f;
; #pragma unroll
;                 for (int bj = 0; bj < 2; ++bj) {
;                     f32x4* p = (f32x4*)(xr + bj * HALF);
;                     const f32x4 o0 = xv[g & 1][rr][bj][0] + acc[ai][bj][m][0] * scale, o1 = xv[g & 1][rr][bj][1] + acc[ai][bj][m][1] * scale;
;                     p[0] = o0; p[1] = o1;
;                     u32x4 w; w.x = cvt_pk_bf16(o0[0], o0[1]); w.y = cvt_pk_bf16(o0[2], o0[3]); w.z = cvt_pk_bf16(o1[0], o1[1]); w.w = cvt_pk_bf16(o1[2], o1[3]);
;                     *(u32x4*)(br + bj * HALF) = w;
;                     ss += (o0[0] * o0[0] + o0[1] * o0[1]) + (o0[2] * o0[2] + o0[3] * o0[3]) + (o1[0] * o1[0] + o1[1] * o1[1]) + (o1[2] * o1[2] + o1[3] * o1[3]);
;                 }
;                 ss += __shfl_xor(ss, 16); ss += __shfl_xor(ss, 32);
;                 if (fq == 0) ssq[(size_t)row * 16 + u.pn * 4 + wc] = ss;
;             }
.LBB0_3256:
	s_or_b64 exec, exec, s[40:41]
	v_add_u32_e32 v180, 0x80, v192
	v_add_u32_e32 v176, 0x90, v192
	v_ashrrev_i32_e32 v181, 31, v180
	v_ashrrev_i32_e32 v177, 31, v176
	v_lshlrev_b64 v[182:183], 12, v[180:181]
	v_lshlrev_b64 v[178:179], 12, v[176:177]
	s_waitcnt lgkmcnt(0)
	v_lshl_add_u64 v[34:35], v[194:195], 0, v[182:183]
	v_lshl_add_u64 v[38:39], v[194:195], 0, v[178:179]
	global_load_dwordx4 v[58:61], v[34:35], off offset:16
	global_load_dwordx4 v[62:65], v[34:35], off
	global_load_dwordx4 v[50:53], v[34:35], off offset:528
	global_load_dwordx4 v[54:57], v[34:35], off offset:512
	global_load_dwordx4 v[42:45], v[38:39], off offset:16
	global_load_dwordx4 v[46:49], v[38:39], off
	s_nop 0
	global_load_dwordx4 v[34:37], v[38:39], off offset:528
	s_nop 0
	global_load_dwordx4 v[38:41], v[38:39], off offset:512
	v_lshl_add_u64 v[184:185], s[8:9], 0, v[218:219]
	v_lshl_add_u64 v[184:185], v[142:143], 2, v[184:185]
	v_pk_add_f32 v[32:33], v[174:175], v[32:33]
	v_pk_add_f32 v[30:31], v[172:173], v[30:31]
	v_pk_add_f32 v[28:29], v[170:171], v[28:29]
	v_pk_add_f32 v[26:27], v[168:169], v[26:27]
	global_store_dwordx4 v[184:185], v[30:33], off
	global_store_dwordx4 v[184:185], v[26:29], off offset:16
	v_cvt_pk_bf16_f32 v168, v30, v31
	v_cvt_pk_bf16_f32 v169, v32, v33
	v_cvt_pk_bf16_f32 v170, v26, v27
	v_pk_add_f32 v[24:25], v[166:167], v[24:25]
	v_mul_f32_e32 v31, v31, v31
	v_fmac_f32_e32 v31, v30, v30
	v_mul_f32_e32 v30, v33, v33
	v_fmac_f32_e32 v30, v32, v32
	v_mul_f32_e32 v27, v27, v27
	v_add_f32_e32 v30, v31, v30
	v_fmac_f32_e32 v27, v26, v26
	v_add_f32_e32 v26, v27, v30
	v_mul_f32_e32 v27, v29, v29
	v_fmac_f32_e32 v27, v28, v28
	v_pk_add_f32 v[22:23], v[164:165], v[22:23]
	v_add_f32_e32 v30, v27, v26
	v_pk_add_f32 v[26:27], v[160:161], v[14:15]
	v_mul_f32_e32 v14, v23, v23
	v_mul_f32_e32 v15, v25, v25
	v_fmac_f32_e32 v14, v22, v22
	v_fmac_f32_e32 v15, v24, v24
	v_add_f32_e32 v14, v14, v15
	v_mul_f32_e32 v15, v27, v27
	v_cvt_pk_bf16_f32 v171, v28, v29
	v_pk_add_f32 v[28:29], v[162:163], v[16:17]
	v_fmac_f32_e32 v15, v26, v26
	v_add_f32_e32 v14, v15, v14
	v_mul_f32_e32 v15, v29, v29
	v_fmac_f32_e32 v15, v28, v28
	v_add_f32_e32 v14, v15, v14
	v_add_f32_e32 v14, v30, v14
	v_mov_b32_e32 v15, v14
	s_nop 1
	v_permlane16_swap_b32 v15, v14
	v_lshlrev_b64 v[186:187], 11, v[214:215]
	v_lshl_add_u64 v[186:187], s[28:29], 0, v[186:187]
	v_lshl_add_u64 v[186:187], v[142:143], 1, v[186:187]
	global_store_dwordx4 v[186:187], v[168:171], off
	global_store_dwordx4 v[184:185], v[22:25], off offset:512
	global_store_dwordx4 v[184:185], v[26:29], off offset:528
	s_waitcnt lgkmcnt(0)
	v_add_f32_e32 v14, v14, v15
	v_mov_b32_e32 v15, v14
	s_nop 1
	v_permlane32_swap_b32 v15, v14
	v_cvt_pk_bf16_f32 v22, v22, v23
	v_cvt_pk_bf16_f32 v23, v24, v25
	v_cvt_pk_bf16_f32 v24, v26, v27
	v_cvt_pk_bf16_f32 v25, v28, v29
	global_store_dwordx4 v[186:187], v[22:25], off offset:256
	s_and_saveexec_b64 s[40:41], s[4:5]
	s_cbranch_execz .LBB0_3258
	v_lshlrev_b64 v[16:17], 6, v[214:215]
	v_lshl_add_u64 v[16:17], s[10:11], 0, v[16:17]
	v_lshl_add_u64 v[16:17], s[38:39], 2, v[16:17]
	s_lshl_b32 s64, s50, 2
	s_mov_b32 s65, s68
	v_lshl_add_u64 v[16:17], v[16:17], 0, s[64:65]
	s_waitcnt lgkmcnt(0)
	v_add_f32_e32 v14, v14, v15
	global_store_dword v[16:17], v14, off
.LBB0_3258:
	s_or_b64 exec, exec, s[40:41]
	s_waitcnt lgkmcnt(0)
	v_lshl_add_u64 v[14:15], s[8:9], 0, v[216:217]
	v_lshl_add_u64 v[22:23], v[142:143], 2, v[14:15]
	v_lshlrev_b64 v[14:15], 11, v[204:205]
	v_lshl_add_u64 v[14:15], s[28:29], 0, v[14:15]
	v_lshl_add_u64 v[24:25], v[142:143], 1, v[14:15]
	v_pk_add_f32 v[16:17], v[158:159], v[20:21]
	v_pk_add_f32 v[14:15], v[156:157], v[18:19]
	v_pk_add_f32 v[12:13], v[154:155], v[12:13]
	v_pk_add_f32 v[10:11], v[152:153], v[10:11]
	global_store_dwordx4 v[22:23], v[14:17], off
	global_store_dwordx4 v[22:23], v[10:13], off offset:16
	v_cvt_pk_bf16_f32 v18, v14, v15
	v_cvt_pk_bf16_f32 v19, v16, v17
	v_cvt_pk_bf16_f32 v20, v10, v11
	v_pk_add_f32 v[8:9], v[150:151], v[8:9]
	v_mul_f32_e32 v15, v15, v15
	v_fmac_f32_e32 v15, v14, v14
	v_mul_f32_e32 v14, v17, v17
	v_fmac_f32_e32 v14, v16, v16
	v_mul_f32_e32 v11, v11, v11
	v_add_f32_e32 v14, v15, v14
	v_fmac_f32_e32 v11, v10, v10
	v_add_f32_e32 v10, v11, v14
	v_mul_f32_e32 v11, v13, v13
	v_fmac_f32_e32 v11, v12, v12
	v_pk_add_f32 v[6:7], v[148:149], v[6:7]
	v_add_f32_e32 v14, v11, v10
	v_pk_add_f32 v[10:11], v[144:145], v[2:3]
	v_mul_f32_e32 v2, v7, v7
	v_mul_f32_e32 v3, v9, v9
	v_fmac_f32_e32 v2, v6, v6
	v_fmac_f32_e32 v3, v8, v8
	v_add_f32_e32 v2, v2, v3
	v_mul_f32_e32 v3, v11, v11
	v_cvt_pk_bf16_f32 v21, v12, v13
	v_pk_add_f32 v[12:13], v[146:147], v[4:5]
	v_fmac_f32_e32 v3, v10, v10
	v_add_f32_e32 v2, v3, v2
	v_mul_f32_e32 v3, v13, v13
	v_fmac_f32_e32 v3, v12, v12
	v_add_f32_e32 v2, v3, v2
	v_add_f32_e32 v2, v14, v2
	v_mov_b32_e32 v3, v2
	s_nop 1
	v_permlane16_swap_b32 v3, v2
	global_store_dwordx4 v[24:25], v[18:21], off
	global_store_dwordx4 v[22:23], v[6:9], off offset:512
	global_store_dwordx4 v[22:23], v[10:13], off offset:528
	v_cvt_pk_bf16_f32 v4, v6, v7
	v_cvt_pk_bf16_f32 v5, v8, v9
	s_waitcnt lgkmcnt(0)
	v_add_f32_e32 v2, v2, v3
	v_mov_b32_e32 v3, v2
	s_nop 1
	v_permlane32_swap_b32 v3, v2
	v_cvt_pk_bf16_f32 v6, v10, v11
	v_cvt_pk_bf16_f32 v7, v12, v13
	global_store_dwordx4 v[24:25], v[4:7], off offset:256
	s_and_saveexec_b64 s[40:41], s[4:5]
	s_cbranch_execz .LBB0_3260
	v_lshlrev_b64 v[4:5], 6, v[204:205]
	v_lshl_add_u64 v[4:5], s[10:11], 0, v[4:5]
	v_lshl_add_u64 v[4:5], s[38:39], 2, v[4:5]
	s_lshl_b32 s64, s50, 2
	s_mov_b32 s65, s68
	v_lshl_add_u64 v[4:5], v[4:5], 0, s[64:65]
	s_waitcnt lgkmcnt(0)
	v_add_f32_e32 v2, v2, v3
	global_store_dword v[4:5], v2, off
; __device__ __forceinline__ unsigned cvt_pk_bf16(float lo, float hi) { unsigned r; asm volatile("v_cvt_pk_bf16_f32 %0, %1, %2" : "=v"(r) : "v"(lo), "v"(hi)); return r; }
;     __device__ __forceinline__ void operator()(const f32x4 (&acc)[2][2][4][2], const Unit& u, int wr, int wc, int fr, int fq) const {
;     ...
;         RESID_LOAD(0, 0);
; #pragma unroll
;         for (int g = 0; g < 4; ++g) {
;             if (g < 3) RESID_LOAD((g + 1) & 1, g + 1);
; #pragma unroll
;             for (int rr = 0; rr < 2; ++rr) {
;                 const int idx = 2 * g + rr, ai = idx >> 2, m = idx & 3;
;                 const int row = row0 + ai * HALF + m * 16;
;                 float* xr = X + (size_t)row * 1024 + col0; bf16_t* br = XB + (size_t)row * 1024 + col0;
;                 float ss = 0.f;
; #pragma unroll
;                 for (int bj = 0; bj < 2; ++bj) {
;                     f32x4* p = (f32x4*)(xr + bj * HALF);
;                     const f32x4 o0 = xv[g & 1][rr][bj][0] + acc[ai][bj][m][0] * scale, o1 = xv[g & 1][rr][bj][1] + acc[ai][bj][m][1] * scale;
;                     p[0] = o0; p[1] = o1;
;                     u32x4 w; w.x = cvt_pk_bf16(o0[0], o0[1]); w.y = cvt_pk_bf16(o0[2], o0[3]); w.z = cvt_pk_bf16(o1[0], o1[1]); w.w = cvt_pk_bf16(o1[2], o1[3]);
;                     *(u32x4*)(br + bj * HALF) = w;
;                     ss += (o0[0] * o0[0] + o0[1] * o0[1]) + (o0[2] * o0[2] + o0[3] * o0[3]) + (o1[0] * o1[0] + o1[1] * o1[1]) + (o1[2] * o1[2] + o1[3] * o1[3]);
;                 }
;                 ss += __shfl_xor(ss, 16); ss += __shfl_xor(ss, 32);
;                 if (fq == 0) ssq[(size_t)row * 16 + u.pn * 4 + wc] = ss;
;             }
.LBB0_3260:
	s_or_b64 exec, exec, s[40:41]
	v_add_u32_e32 v148, 0xa0, v192
	v_add_u32_e32 v144, 0xb0, v192
	v_ashrrev_i32_e32 v149, 31, v148
	v_ashrrev_i32_e32 v145, 31, v144
	v_lshlrev_b64 v[150:151], 12, v[148:149]
	v_lshlrev_b64 v[146:147], 12, v[144:145]
	s_waitcnt lgkmcnt(0)
	v_lshl_add_u64 v[2:3], v[194:195], 0, v[150:151]
	v_lshl_add_u64 v[6:7], v[194:195], 0, v[146:147]
	global_load_dwordx4 v[26:29], v[2:3], off offset:16
	global_load_dwordx4 v[30:33], v[2:3], off
	global_load_dwordx4 v[18:21], v[2:3], off offset:528
	global_load_dwordx4 v[22:25], v[2:3], off offset:512
	global_load_dwordx4 v[10:13], v[6:7], off offset:16
	global_load_dwordx4 v[14:17], v[6:7], off
	s_nop 0
	global_load_dwordx4 v[2:5], v[6:7], off offset:528
	s_nop 0
	global_load_dwordx4 v[6:9], v[6:7], off offset:512
	v_lshl_add_u64 v[152:153], s[8:9], 0, v[182:183]
	v_lshl_add_u64 v[152:153], v[142:143], 2, v[152:153]
	s_waitcnt vmcnt(26)
	v_pk_add_f32 v[64:65], v[128:129], v[64:65]
	v_pk_add_f32 v[62:63], v[126:127], v[62:63]
	v_pk_add_f32 v[60:61], v[124:125], v[60:61]
	v_pk_add_f32 v[58:59], v[122:123], v[58:59]
	global_store_dwordx4 v[152:153], v[62:65], off
	global_store_dwordx4 v[152:153], v[58:61], off offset:16
	v_cvt_pk_bf16_f32 v122, v62, v63
	v_cvt_pk_bf16_f32 v123, v64, v65
	v_cvt_pk_bf16_f32 v124, v58, v59
	s_waitcnt vmcnt(26)
	v_pk_add_f32 v[56:57], v[120:121], v[56:57]
	v_mul_f32_e32 v63, v63, v63
	v_fmac_f32_e32 v63, v62, v62
	v_mul_f32_e32 v62, v65, v65
	v_fmac_f32_e32 v62, v64, v64
	v_mul_f32_e32 v59, v59, v59
	v_add_f32_e32 v62, v63, v62
	v_fmac_f32_e32 v59, v58, v58
	v_add_f32_e32 v58, v59, v62
	v_mul_f32_e32 v59, v61, v61
	v_fmac_f32_e32 v59, v60, v60
	v_pk_add_f32 v[54:55], v[118:119], v[54:55]
	v_add_f32_e32 v62, v59, v58
	v_pk_add_f32 v[58:59], v[114:115], v[50:51]
	v_mul_f32_e32 v50, v55, v55
	v_mul_f32_e32 v51, v57, v57
	v_fmac_f32_e32 v50, v54, v54
	v_fmac_f32_e32 v51, v56, v56
	v_add_f32_e32 v50, v50, v51
	v_mul_f32_e32 v51, v59, v59
	v_cvt_pk_bf16_f32 v125, v60, v61
	v_pk_add_f32 v[60:61], v[116:117], v[52:53]
	v_fmac_f32_e32 v51, v58, v58
	v_add_f32_e32 v50, v51, v50
	v_mul_f32_e32 v51, v61, v61
	v_fmac_f32_e32 v51, v60, v60
	v_add_f32_e32 v50, v51, v50
	v_add_f32_e32 v50, v62, v50
	v_mov_b32_e32 v51, v50
	s_nop 1
	v_permlane16_swap_b32 v51, v50
	v_lshlrev_b64 v[154:155], 11, v[180:181]
	v_lshl_add_u64 v[154:155], s[28:29], 0, v[154:155]
	v_lshl_add_u64 v[154:155], v[142:143], 1, v[154:155]
	global_store_dwordx4 v[154:155], v[122:125], off
	global_store_dwordx4 v[152:153], v[54:57], off offset:512
	global_store_dwordx4 v[152:153], v[58:61], off offset:528
	s_waitcnt lgkmcnt(0)
	v_add_f32_e32 v50, v50, v51
	v_mov_b32_e32 v51, v50
	s_nop 1
	v_permlane32_swap_b32 v51, v50
	v_cvt_pk_bf16_f32 v52, v54, v55
	v_cvt_pk_bf16_f32 v53, v56, v57
	v_cvt_pk_bf16_f32 v54, v58, v59
	v_cvt_pk_bf16_f32 v55, v60, v61
	global_store_dwordx4 v[154:155], v[52:55], off offset:256
	s_and_saveexec_b64 s[40:41], s[4:5]
	s_cbranch_execz .LBB0_3262
	v_lshlrev_b64 v[52:53], 6, v[180:181]
	v_lshl_add_u64 v[52:53], s[10:11], 0, v[52:53]
	v_lshl_add_u64 v[52:53], s[38:39], 2, v[52:53]
	s_lshl_b32 s64, s50, 2
	s_mov_b32 s65, s68
	v_lshl_add_u64 v[52:53], v[52:53], 0, s[64:65]
	s_waitcnt lgkmcnt(0)
	v_add_f32_e32 v50, v50, v51
	global_store_dword v[52:53], v50, off
.LBB0_3262:
	s_or_b64 exec, exec, s[40:41]
	s_waitcnt lgkmcnt(0)
	v_lshl_add_u64 v[50:51], s[8:9], 0, v[178:179]
	v_lshl_add_u64 v[54:55], v[142:143], 2, v[50:51]
	v_lshlrev_b64 v[50:51], 11, v[176:177]
	v_lshl_add_u64 v[50:51], s[28:29], 0, v[50:51]
	s_waitcnt vmcnt(28)
	v_pk_add_f32 v[48:49], v[112:113], v[48:49]
	v_pk_add_f32 v[46:47], v[110:111], v[46:47]
	v_lshl_add_u64 v[56:57], v[142:143], 1, v[50:51]
	v_pk_add_f32 v[44:45], v[108:109], v[44:45]
	v_pk_add_f32 v[42:43], v[106:107], v[42:43]
	global_store_dwordx4 v[54:55], v[46:49], off
	global_store_dwordx4 v[54:55], v[42:45], off offset:16
	v_cvt_pk_bf16_f32 v50, v46, v47
	v_cvt_pk_bf16_f32 v51, v48, v49
	v_cvt_pk_bf16_f32 v52, v42, v43
	s_waitcnt vmcnt(28)
	v_pk_add_f32 v[40:41], v[104:105], v[40:41]
	v_mul_f32_e32 v47, v47, v47
	v_fmac_f32_e32 v47, v46, v46
	v_mul_f32_e32 v46, v49, v49
	v_fmac_f32_e32 v46, v48, v48
	v_mul_f32_e32 v43, v43, v43
	v_add_f32_e32 v46, v47, v46
	v_fmac_f32_e32 v43, v42, v42
	v_add_f32_e32 v42, v43, v46
	v_mul_f32_e32 v43, v45, v45
	v_fmac_f32_e32 v43, v44, v44
	v_pk_add_f32 v[38:39], v[102:103], v[38:39]
	v_add_f32_e32 v46, v43, v42
	v_pk_add_f32 v[42:43], v[98:99], v[34:35]
	v_mul_f32_e32 v34, v39, v39
	v_mul_f32_e32 v35, v41, v41
	v_fmac_f32_e32 v34, v38, v38
	v_fmac_f32_e32 v35, v40, v40
	v_add_f32_e32 v34, v34, v35
	v_mul_f32_e32 v35, v43, v43
	v_cvt_pk_bf16_f32 v53, v44, v45
	v_pk_add_f32 v[44:45], v[100:101], v[36:37]
	v_fmac_f32_e32 v35, v42, v42
	v_add_f32_e32 v34, v35, v34
	v_mul_f32_e32 v35, v45, v45
	v_fmac_f32_e32 v35, v44, v44
	v_add_f32_e32 v34, v35, v34
	v_add_f32_e32 v34, v46, v34
	v_mov_b32_e32 v35, v34
	s_nop 1
	v_permlane16_swap_b32 v35, v34
	global_store_dwordx4 v[56:57], v[50:53], off
	global_store_dwordx4 v[54:55], v[38:41], off offset:512
	global_store_dwordx4 v[54:55], v[42:45], off offset:528
	v_cvt_pk_bf16_f32 v36, v38, v39
	v_cvt_pk_bf16_f32 v37, v40, v41
	s_waitcnt lgkmcnt(0)
	v_add_f32_e32 v34, v34, v35
	v_mov_b32_e32 v35, v34
	s_nop 1
	v_permlane32_swap_b32 v35, v34
	v_cvt_pk_bf16_f32 v38, v42, v43
	v_cvt_pk_bf16_f32 v39, v44, v45
	global_store_dwordx4 v[56:57], v[36:39], off offset:256
	s_and_saveexec_b64 s[40:41], s[4:5]
	s_cbranch_execz .LBB0_3264
	v_lshlrev_b64 v[36:37], 6, v[176:177]
	v_lshl_add_u64 v[36:37], s[10:11], 0, v[36:37]
	v_lshl_add_u64 v[36:37], s[38:39], 2, v[36:37]
	s_lshl_b32 s64, s50, 2
	s_mov_b32 s65, s68
	v_lshl_add_u64 v[36:37], v[36:37], 0, s[64:65]
	s_waitcnt lgkmcnt(0)
	v_add_f32_e32 v34, v34, v35
	global_store_dword v[36:37], v34, off
; __device__ __forceinline__ unsigned cvt_pk_bf16(float lo, float hi) { unsigned r; asm volatile("v_cvt_pk_bf16_f32 %0, %1, %2" : "=v"(r) : "v"(lo), "v"(hi)); return r; }
;     __device__ __forceinline__ void operator()(const f32x4 (&acc)[2][2][4][2], const Unit& u, int wr, int wc, int fr, int fq) const {
;     ...
;             for (int rr = 0; rr < 2; ++rr) {
;                 const int idx = 2 * g + rr, ai = idx >> 2, m = idx & 3;
;                 const int row = row0 + ai * HALF + m * 16;
;                 float* xr = X + (size_t)row * 1024 + col0; bf16_t* br = XB + (size_t)row * 1024 + col0;
;                 float ss = 0.f;
; #pragma unroll
;                 for (int bj = 0; bj < 2; ++bj) {
;                     f32x4* p = (f32x4*)(xr + bj * HALF);
;                     const f32x4 o0 = xv[g & 1][rr][bj][0] + acc[ai][bj][m][0] * scale, o1 = xv[g & 1][rr][bj][1] + acc[ai][bj][m][1] * scale;
;                     p[0] = o0; p[1] = o1;
;                     u32x4 w; w.x = cvt_pk_bf16(o0[0], o0[1]); w.y = cvt_pk_bf16(o0[2], o0[3]); w.z = cvt_pk_bf16(o1[0], o1[1]); w.w = cvt_pk_bf16(o1[2], o1[3]);
;                     *(u32x4*)(br + bj * HALF) = w;
;                     ss += (o0[0] * o0[0] + o0[1] * o0[1]) + (o0[2] * o0[2] + o0[3] * o0[3]) + (o1[0] * o1[0] + o1[1] * o1[1]) + (o1[2] * o1[2] + o1[3] * o1[3]);
;                 }
;                 ss += __shfl_xor(ss, 16); ss += __shfl_xor(ss, 32);
;                 if (fq == 0) ssq[(size_t)row * 16 + u.pn * 4 + wc] = ss;
;             }
.LBB0_3264:
	s_or_b64 exec, exec, s[40:41]
	s_waitcnt lgkmcnt(0)
	v_lshl_add_u64 v[34:35], s[8:9], 0, v[150:151]
	v_lshl_add_u64 v[38:39], v[142:143], 2, v[34:35]
	v_lshlrev_b64 v[34:35], 11, v[148:149]
	v_lshl_add_u64 v[34:35], s[28:29], 0, v[34:35]
	s_waitcnt vmcnt(18)
	v_pk_add_f32 v[32:33], v[96:97], v[32:33]
	v_pk_add_f32 v[30:31], v[94:95], v[30:31]
	v_lshl_add_u64 v[40:41], v[142:143], 1, v[34:35]
	v_pk_add_f32 v[28:29], v[92:93], v[28:29]
	v_pk_add_f32 v[26:27], v[90:91], v[26:27]
	global_store_dwordx4 v[38:39], v[30:33], off
	global_store_dwordx4 v[38:39], v[26:29], off offset:16
	v_cvt_pk_bf16_f32 v34, v30, v31
	v_cvt_pk_bf16_f32 v35, v32, v33
	v_cvt_pk_bf16_f32 v36, v26, v27
	s_waitcnt vmcnt(18)
	v_pk_add_f32 v[24:25], v[88:89], v[24:25]
	v_mul_f32_e32 v31, v31, v31
	v_fmac_f32_e32 v31, v30, v30
	v_mul_f32_e32 v30, v33, v33
	v_fmac_f32_e32 v30, v32, v32
	v_mul_f32_e32 v27, v27, v27
	v_add_f32_e32 v30, v31, v30
	v_fmac_f32_e32 v27, v26, v26
	v_add_f32_e32 v26, v27, v30
	v_mul_f32_e32 v27, v29, v29
	v_fmac_f32_e32 v27, v28, v28
	v_pk_add_f32 v[22:23], v[86:87], v[22:23]
	v_add_f32_e32 v30, v27, v26
	v_pk_add_f32 v[26:27], v[82:83], v[18:19]
	v_mul_f32_e32 v18, v23, v23
	v_mul_f32_e32 v19, v25, v25
	v_fmac_f32_e32 v18, v22, v22
	v_fmac_f32_e32 v19, v24, v24
	v_add_f32_e32 v18, v18, v19
	v_mul_f32_e32 v19, v27, v27
	v_cvt_pk_bf16_f32 v37, v28, v29
	v_pk_add_f32 v[28:29], v[84:85], v[20:21]
	v_fmac_f32_e32 v19, v26, v26
	v_add_f32_e32 v18, v19, v18
	v_mul_f32_e32 v19, v29, v29
	v_fmac_f32_e32 v19, v28, v28
	v_add_f32_e32 v18, v19, v18
	v_add_f32_e32 v18, v30, v18
	v_mov_b32_e32 v19, v18
	s_nop 1
	v_permlane16_swap_b32 v19, v18
	global_store_dwordx4 v[40:41], v[34:37], off
	global_store_dwordx4 v[38:39], v[22:25], off offset:512
	global_store_dwordx4 v[38:39], v[26:29], off offset:528
	v_cvt_pk_bf16_f32 v20, v22, v23
	v_cvt_pk_bf16_f32 v21, v24, v25
	s_waitcnt lgkmcnt(0)
	v_add_f32_e32 v18, v18, v19
	v_mov_b32_e32 v19, v18
	s_nop 1
	v_permlane32_swap_b32 v19, v18
	v_cvt_pk_bf16_f32 v22, v26, v27
	v_cvt_pk_bf16_f32 v23, v28, v29
	global_store_dwordx4 v[40:41], v[20:23], off offset:256
	s_and_saveexec_b64 s[40:41], s[4:5]
	s_cbranch_execz .LBB0_3266
	v_lshlrev_b64 v[20:21], 6, v[148:149]
	v_lshl_add_u64 v[20:21], s[10:11], 0, v[20:21]
	v_lshl_add_u64 v[20:21], s[38:39], 2, v[20:21]
	s_lshl_b32 s64, s50, 2
	s_mov_b32 s65, s68
	v_lshl_add_u64 v[20:21], v[20:21], 0, s[64:65]
	s_waitcnt lgkmcnt(0)
	v_add_f32_e32 v18, v18, v19
	global_store_dword v[20:21], v18, off
.LBB0_3266:
	s_or_b64 exec, exec, s[40:41]
	s_waitcnt lgkmcnt(0)
	v_lshl_add_u64 v[18:19], s[8:9], 0, v[146:147]
	v_lshl_add_u64 v[22:23], v[142:143], 2, v[18:19]
	v_lshlrev_b64 v[18:19], 11, v[144:145]
	v_lshl_add_u64 v[18:19], s[28:29], 0, v[18:19]
	s_waitcnt vmcnt(20)
	v_pk_add_f32 v[16:17], v[80:81], v[16:17]
	v_pk_add_f32 v[14:15], v[78:79], v[14:15]
	v_lshl_add_u64 v[24:25], v[142:143], 1, v[18:19]
	v_pk_add_f32 v[12:13], v[76:77], v[12:13]
	v_pk_add_f32 v[10:11], v[74:75], v[10:11]
	global_store_dwordx4 v[22:23], v[14:17], off
	global_store_dwordx4 v[22:23], v[10:13], off offset:16
	v_cvt_pk_bf16_f32 v18, v14, v15
	v_cvt_pk_bf16_f32 v19, v16, v17
	v_cvt_pk_bf16_f32 v20, v10, v11
	s_waitcnt vmcnt(20)
	v_pk_add_f32 v[8:9], v[72:73], v[8:9]
	v_mul_f32_e32 v15, v15, v15
	v_fmac_f32_e32 v15, v14, v14
	v_mul_f32_e32 v14, v17, v17
	v_fmac_f32_e32 v14, v16, v16
	v_mul_f32_e32 v11, v11, v11
	v_add_f32_e32 v14, v15, v14
	v_fmac_f32_e32 v11, v10, v10
	v_add_f32_e32 v10, v11, v14
	v_mul_f32_e32 v11, v13, v13
	v_fmac_f32_e32 v11, v12, v12
	v_pk_add_f32 v[6:7], v[70:71], v[6:7]
	v_add_f32_e32 v14, v11, v10
	v_pk_add_f32 v[10:11], v[66:67], v[2:3]
	v_mul_f32_e32 v2, v7, v7
	v_mul_f32_e32 v3, v9, v9
	v_fmac_f32_e32 v2, v6, v6
	v_fmac_f32_e32 v3, v8, v8
	v_add_f32_e32 v2, v2, v3
	v_mul_f32_e32 v3, v11, v11
	v_cvt_pk_bf16_f32 v21, v12, v13
	v_pk_add_f32 v[12:13], v[68:69], v[4:5]
	v_fmac_f32_e32 v3, v10, v10
	v_add_f32_e32 v2, v3, v2
	v_mul_f32_e32 v3, v13, v13
	v_fmac_f32_e32 v3, v12, v12
	v_add_f32_e32 v2, v3, v2
	v_add_f32_e32 v2, v14, v2
	v_mov_b32_e32 v3, v2
	s_nop 1
	v_permlane16_swap_b32 v3, v2
	global_store_dwordx4 v[24:25], v[18:21], off
	global_store_dwordx4 v[22:23], v[6:9], off offset:512
	global_store_dwordx4 v[22:23], v[10:13], off offset:528
	v_cvt_pk_bf16_f32 v4, v6, v7
	v_cvt_pk_bf16_f32 v5, v8, v9
	s_waitcnt lgkmcnt(0)
	v_add_f32_e32 v2, v2, v3
	v_mov_b32_e32 v3, v2
	s_nop 1
	v_permlane32_swap_b32 v3, v2
	v_cvt_pk_bf16_f32 v6, v10, v11
	v_cvt_pk_bf16_f32 v7, v12, v13
	global_store_dwordx4 v[24:25], v[4:7], off offset:256
	s_and_saveexec_b64 s[40:41], s[4:5]
	s_cbranch_execz .LBB0_3268
	v_lshlrev_b64 v[4:5], 6, v[144:145]
	v_lshl_add_u64 v[4:5], s[10:11], 0, v[4:5]
	v_lshl_add_u64 v[4:5], s[38:39], 2, v[4:5]
	s_lshl_b32 s38, s50, 2
	s_mov_b32 s39, s68
	v_lshl_add_u64 v[4:5], v[4:5], 0, s[38:39]
	s_waitcnt lgkmcnt(0)
	v_add_f32_e32 v2, v2, v3
	global_store_dword v[4:5], v2, off

; __device__ __forceinline__ unsigned cvt_pk_bf16(float lo, float hi) { unsigned r; asm volatile("v_cvt_pk_bf16_f32 %0, %1, %2" : "=v"(r) : "v"(lo), "v"(hi)); return r; }
;     __device__ __forceinline__ void operator()(const f32x4 (&acc)[2][2][4][2], const Unit& u, int wr, int wc, int fr, int fq) const {
;         const int row0 = u.pm * BM + wr * 64 + fr, col0 = u.pn * BM + wc * 32 + 8 * fq;
;         f32x4 xv[2][2][2][2];
;     ...
;         RESID_LOAD(0, 0);
; #pragma unroll
;         for (int g = 0; g < 4; ++g) {
;             if (g < 3) RESID_LOAD((g + 1) & 1, g + 1);
; #pragma unroll
;             for (int rr = 0; rr < 2; ++rr) {
;                 const int idx = 2 * g + rr, ai = idx >> 2, m = idx & 3;
;                 const int row = row0 + ai * HALF + m * 16;
;                 float* xr = X + (size_t)row * 1024 + col0; bf16_t* br = XB + (size_t)row * 1024 + col0;
;                 float ss = 0.f;
; #pragma unroll
;                 for (int bj = 0; bj < 2; ++bj) {
;                     f32x4* p = (f32x4*)(xr + bj * HALF);
;                     const f32x4 o0 = xv[g & 1][rr][bj][0] + acc[ai][bj][m][0] * scale, o1 = xv[g & 1][rr][bj][1] + acc[ai][bj][m][1] * scale;
;                     p[0] = o0; p[1] = o1;
;                     u32x4 w; w.x = cvt_pk_bf16(o0[0], o0[1]); w.y = cvt_pk_bf16(o0[2], o0[3]); w.z = cvt_pk_bf16(o1[0], o1[1]); w.w = cvt_pk_bf16(o1[2], o1[3]);
;                     *(u32x4*)(br + bj * HALF) = w;
;                     ss += (o0[0] * o0[0] + o0[1] * o0[1]) + (o0[2] * o0[2] + o0[3] * o0[3]) + (o1[0] * o1[0] + o1[1] * o1[1]) + (o1[2] * o1[2] + o1[3] * o1[3]);
;                 }
;                 ss += __shfl_xor(ss, 16); ss += __shfl_xor(ss, 32);
;                 if (fq == 0) ssq[(size_t)row * 16 + u.pn * 4 + wc] = ss;
;             }
.LBB0_3992:
	v_lshl_or_b32 v198, s57, 8, v217
	v_lshl_add_u32 v200, s58, 8, v1
	v_ashrrev_i32_e32 v199, 31, v198
	v_lshlrev_b64 v[228:229], 2, v[198:199]
	v_ashrrev_i32_e32 v201, 31, v200
	v_lshl_add_u64 v[202:203], s[8:9], 0, v[228:229]
	v_lshlrev_b64 v[250:251], 12, v[200:201]
	v_lshl_add_u64 v[130:131], v[202:203], 0, v[250:251]
	global_load_dwordx4 v[242:245], v[130:131], off offset:16
	global_load_dwordx4 v[246:249], v[130:131], off
	global_load_dwordx4 v[178:181], v[130:131], off offset:528
	global_load_dwordx4 v[182:185], v[130:131], off offset:512
	v_or_b32_e32 v210, 16, v200
	v_ashrrev_i32_e32 v211, 31, v210
	v_or_b32_e32 v206, 32, v200
	v_or_b32_e32 v204, 48, v200
	v_lshlrev_b64 v[214:215], 12, v[210:211]
	v_ashrrev_i32_e32 v207, 31, v206
	v_ashrrev_i32_e32 v205, 31, v204
	v_lshl_add_u64 v[130:131], v[202:203], 0, v[214:215]
	v_lshlrev_b64 v[212:213], 12, v[206:207]
	v_lshlrev_b64 v[208:209], 12, v[204:205]
	global_load_dwordx4 v[170:173], v[130:131], off offset:16
	global_load_dwordx4 v[174:177], v[130:131], off
	global_load_dwordx4 v[162:165], v[130:131], off offset:528
	global_load_dwordx4 v[166:169], v[130:131], off offset:512
	v_lshl_add_u64 v[130:131], v[202:203], 0, v[212:213]
	v_lshl_add_u64 v[134:135], v[202:203], 0, v[208:209]
	global_load_dwordx4 v[154:157], v[130:131], off offset:16
	global_load_dwordx4 v[158:161], v[130:131], off
	global_load_dwordx4 v[142:145], v[130:131], off offset:528
	global_load_dwordx4 v[150:153], v[130:131], off offset:512
	global_load_dwordx4 v[138:141], v[134:135], off offset:16
	global_load_dwordx4 v[146:149], v[134:135], off
	s_nop 0
	global_load_dwordx4 v[130:133], v[134:135], off offset:528
	s_nop 0
	global_load_dwordx4 v[134:137], v[134:135], off offset:512
	v_lshl_add_u64 v[250:251], s[8:9], 0, v[250:251]
	v_lshl_add_u64 v[228:229], v[250:251], 0, v[228:229]
	v_lshlrev_b64 v[250:251], 11, v[200:201]
	v_lshl_add_u64 v[250:251], s[22:23], 0, v[250:251]
	v_lshl_add_u64 v[250:251], v[198:199], 1, v[250:251]
	s_lshl_b32 s30, s57, 2
	s_ashr_i32 s31, s30, 31
	s_waitcnt vmcnt(0)
	v_pk_add_f32 v[124:125], v[124:125], v[244:245]
	v_pk_add_f32 v[128:129], v[128:129], v[248:249]
	v_pk_add_f32 v[126:127], v[126:127], v[246:247]
	v_pk_add_f32 v[122:123], v[122:123], v[242:243]
	global_store_dwordx4 v[228:229], v[126:129], off
	global_store_dwordx4 v[228:229], v[122:125], off offset:16
	v_cvt_pk_bf16_f32 v242, v126, v127
	v_cvt_pk_bf16_f32 v243, v128, v129
	v_cvt_pk_bf16_f32 v244, v122, v123
	v_pk_add_f32 v[120:121], v[120:121], v[184:185]
	v_mul_f32_e32 v127, v127, v127
	v_fmac_f32_e32 v127, v126, v126
	v_mul_f32_e32 v126, v129, v129
	v_fmac_f32_e32 v126, v128, v128
	v_mul_f32_e32 v123, v123, v123
	v_add_f32_e32 v126, v127, v126
	v_fmac_f32_e32 v123, v122, v122
	v_add_f32_e32 v122, v123, v126
	v_mul_f32_e32 v123, v125, v125
	v_fmac_f32_e32 v123, v124, v124
	v_pk_add_f32 v[118:119], v[118:119], v[182:183]
	v_cvt_pk_bf16_f32 v245, v124, v125
	global_store_dwordx4 v[250:251], v[242:245], off
	v_add_f32_e32 v126, v123, v122
	v_pk_add_f32 v[116:117], v[116:117], v[180:181]
	v_pk_add_f32 v[114:115], v[114:115], v[178:179]
	global_store_dwordx4 v[228:229], v[118:121], off offset:512
	global_store_dwordx4 v[228:229], v[114:117], off offset:528
	v_cvt_pk_bf16_f32 v122, v118, v119
	v_cvt_pk_bf16_f32 v123, v120, v121
	v_cvt_pk_bf16_f32 v124, v114, v115
	v_cvt_pk_bf16_f32 v125, v116, v117
	s_nop 0
	v_mul_f32_e32 v119, v119, v119
	v_fmac_f32_e32 v119, v118, v118
	v_mul_f32_e32 v118, v121, v121
	v_fmac_f32_e32 v118, v120, v120
	v_mul_f32_e32 v115, v115, v115
	v_add_f32_e32 v118, v119, v118
	v_fmac_f32_e32 v115, v114, v114
	v_add_f32_e32 v114, v115, v118
	v_mul_f32_e32 v115, v117, v117
	v_fmac_f32_e32 v115, v116, v116
	v_add_f32_e32 v114, v115, v114
	v_add_f32_e32 v114, v126, v114
	v_mov_b32_e32 v115, v114
	s_nop 1
	v_permlane16_swap_b32 v115, v114
	global_store_dwordx4 v[250:251], v[122:125], off offset:256
	s_waitcnt lgkmcnt(0)
	v_add_f32_e32 v114, v114, v115
	v_mov_b32_e32 v115, v114
	s_nop 1
	v_permlane32_swap_b32 v115, v114
	s_and_saveexec_b64 s[34:35], s[4:5]
	s_cbranch_execz .LBB0_3994
	v_lshlrev_b64 v[116:117], 6, v[200:201]
	v_lshl_add_u64 v[116:117], s[10:11], 0, v[116:117]
	v_lshl_add_u64 v[116:117], s[30:31], 2, v[116:117]
	s_lshl_b32 s58, s44, 2
	s_mov_b32 s59, s68
	v_lshl_add_u64 v[116:117], v[116:117], 0, s[58:59]
	s_waitcnt lgkmcnt(0)
	v_add_f32_e32 v114, v114, v115
	global_store_dword v[116:117], v114, off
; __device__ __forceinline__ unsigned cvt_pk_bf16(float lo, float hi) { unsigned r; asm volatile("v_cvt_pk_bf16_f32 %0, %1, %2" : "=v"(r) : "v"(lo), "v"(hi)); return r; }
;     __device__ __forceinline__ void operator()(const f32x4 (&acc)[2][2][4][2], const Unit& u, int wr, int wc, int fr, int fq) const {
;     ...
;             if (g < 3) RESID_LOAD((g + 1) & 1, g + 1);
; #pragma unroll
;             for (int rr = 0; rr < 2; ++rr) {
;                 const int idx = 2 * g + rr, ai = idx >> 2, m = idx & 3;
;                 const int row = row0 + ai * HALF + m * 16;
;                 float* xr = X + (size_t)row * 1024 + col0; bf16_t* br = XB + (size_t)row * 1024 + col0;
;                 float ss = 0.f;
; #pragma unroll
;                 for (int bj = 0; bj < 2; ++bj) {
;                     f32x4* p = (f32x4*)(xr + bj * HALF);
;                     const f32x4 o0 = xv[g & 1][rr][bj][0] + acc[ai][bj][m][0] * scale, o1 = xv[g & 1][rr][bj][1] + acc[ai][bj][m][1] * scale;
;                     p[0] = o0; p[1] = o1;
;                     u32x4 w; w.x = cvt_pk_bf16(o0[0], o0[1]); w.y = cvt_pk_bf16(o0[2], o0[3]); w.z = cvt_pk_bf16(o1[0], o1[1]); w.w = cvt_pk_bf16(o1[2], o1[3]);
;                     *(u32x4*)(br + bj * HALF) = w;
;                     ss += (o0[0] * o0[0] + o0[1] * o0[1]) + (o0[2] * o0[2] + o0[3] * o0[3]) + (o1[0] * o1[0] + o1[1] * o1[1]) + (o1[2] * o1[2] + o1[3] * o1[3]);
;                 }
;                 ss += __shfl_xor(ss, 16); ss += __shfl_xor(ss, 32);
;                 if (fq == 0) ssq[(size_t)row * 16 + u.pn * 4 + wc] = ss;
;             }
.LBB0_3994:
	s_or_b64 exec, exec, s[34:35]
	s_waitcnt lgkmcnt(0)
	v_lshl_add_u64 v[114:115], s[8:9], 0, v[214:215]
	v_lshl_add_u64 v[118:119], v[198:199], 2, v[114:115]
	v_lshlrev_b64 v[114:115], 11, v[210:211]
	v_lshl_add_u64 v[114:115], s[22:23], 0, v[114:115]
	v_pk_add_f32 v[112:113], v[112:113], v[176:177]
	v_pk_add_f32 v[110:111], v[110:111], v[174:175]
	v_lshl_add_u64 v[120:121], v[198:199], 1, v[114:115]
	v_pk_add_f32 v[108:109], v[108:109], v[172:173]
	v_pk_add_f32 v[106:107], v[106:107], v[170:171]
	global_store_dwordx4 v[118:119], v[110:113], off
	global_store_dwordx4 v[118:119], v[106:109], off offset:16
	v_cvt_pk_bf16_f32 v114, v110, v111
	v_cvt_pk_bf16_f32 v115, v112, v113
	v_cvt_pk_bf16_f32 v116, v106, v107
	v_pk_add_f32 v[104:105], v[104:105], v[168:169]
	v_mul_f32_e32 v111, v111, v111
	v_fmac_f32_e32 v111, v110, v110
	v_mul_f32_e32 v110, v113, v113
	v_fmac_f32_e32 v110, v112, v112
	v_mul_f32_e32 v107, v107, v107
	v_add_f32_e32 v110, v111, v110
	v_fmac_f32_e32 v107, v106, v106
	v_add_f32_e32 v106, v107, v110
	v_mul_f32_e32 v107, v109, v109
	v_fmac_f32_e32 v107, v108, v108
	v_pk_add_f32 v[102:103], v[102:103], v[166:167]
	v_add_f32_e32 v110, v107, v106
	v_pk_add_f32 v[106:107], v[98:99], v[162:163]
	v_mul_f32_e32 v98, v103, v103
	v_mul_f32_e32 v99, v105, v105
	v_fmac_f32_e32 v98, v102, v102
	v_fmac_f32_e32 v99, v104, v104
	v_add_f32_e32 v98, v98, v99
	v_mul_f32_e32 v99, v107, v107
	v_cvt_pk_bf16_f32 v117, v108, v109
	v_pk_add_f32 v[108:109], v[100:101], v[164:165]
	v_fmac_f32_e32 v99, v106, v106
	v_add_f32_e32 v98, v99, v98
	v_mul_f32_e32 v99, v109, v109
	v_fmac_f32_e32 v99, v108, v108
	v_add_f32_e32 v98, v99, v98
	v_add_f32_e32 v98, v110, v98
	v_mov_b32_e32 v99, v98
	s_nop 1
	v_permlane16_swap_b32 v99, v98
	global_store_dwordx4 v[120:121], v[114:117], off
	global_store_dwordx4 v[118:119], v[102:105], off offset:512
	global_store_dwordx4 v[118:119], v[106:109], off offset:528
	v_cvt_pk_bf16_f32 v100, v102, v103
	v_cvt_pk_bf16_f32 v101, v104, v105
	s_waitcnt lgkmcnt(0)
	v_add_f32_e32 v98, v98, v99
	v_mov_b32_e32 v99, v98
	s_nop 1
	v_permlane32_swap_b32 v99, v98
	v_cvt_pk_bf16_f32 v102, v106, v107
	v_cvt_pk_bf16_f32 v103, v108, v109
	global_store_dwordx4 v[120:121], v[100:103], off offset:256
	s_and_saveexec_b64 s[34:35], s[4:5]
	s_cbranch_execz .LBB0_3996
	v_lshlrev_b64 v[100:101], 6, v[210:211]
	v_lshl_add_u64 v[100:101], s[10:11], 0, v[100:101]
	v_lshl_add_u64 v[100:101], s[30:31], 2, v[100:101]
	s_lshl_b32 s58, s44, 2
	s_mov_b32 s59, s68
	v_lshl_add_u64 v[100:101], v[100:101], 0, s[58:59]
	s_waitcnt lgkmcnt(0)
	v_add_f32_e32 v98, v98, v99
	global_store_dword v[100:101], v98, off
.LBB0_3996:
	s_or_b64 exec, exec, s[34:35]
	v_add_u32_e32 v166, 0x80, v200
	v_add_u32_e32 v162, 0x90, v200
	v_ashrrev_i32_e32 v167, 31, v166
	v_ashrrev_i32_e32 v163, 31, v162
	v_lshlrev_b64 v[168:169], 12, v[166:167]
	v_lshlrev_b64 v[164:165], 12, v[162:163]
	s_waitcnt lgkmcnt(0)
	v_lshl_add_u64 v[98:99], v[202:203], 0, v[168:169]
	v_lshl_add_u64 v[102:103], v[202:203], 0, v[164:165]
	global_load_dwordx4 v[122:125], v[98:99], off offset:16
	global_load_dwordx4 v[126:129], v[98:99], off
	global_load_dwordx4 v[114:117], v[98:99], off offset:528
	global_load_dwordx4 v[118:121], v[98:99], off offset:512
	global_load_dwordx4 v[106:109], v[102:103], off offset:16
	global_load_dwordx4 v[110:113], v[102:103], off
	s_nop 0
	global_load_dwordx4 v[98:101], v[102:103], off offset:528
	s_nop 0
	global_load_dwordx4 v[102:105], v[102:103], off offset:512
	v_lshl_add_u64 v[170:171], s[8:9], 0, v[212:213]
	v_lshl_add_u64 v[170:171], v[198:199], 2, v[170:171]
	v_pk_add_f32 v[96:97], v[96:97], v[160:161]
	v_pk_add_f32 v[94:95], v[94:95], v[158:159]
	v_pk_add_f32 v[92:93], v[92:93], v[156:157]
	v_pk_add_f32 v[90:91], v[90:91], v[154:155]
	global_store_dwordx4 v[170:171], v[94:97], off
	global_store_dwordx4 v[170:171], v[90:93], off offset:16
	v_cvt_pk_bf16_f32 v154, v94, v95
	v_cvt_pk_bf16_f32 v155, v96, v97
	v_cvt_pk_bf16_f32 v156, v90, v91
	v_pk_add_f32 v[88:89], v[88:89], v[152:153]
	v_mul_f32_e32 v95, v95, v95
	v_fmac_f32_e32 v95, v94, v94
	v_mul_f32_e32 v94, v97, v97
	v_fmac_f32_e32 v94, v96, v96
	v_mul_f32_e32 v91, v91, v91
	v_add_f32_e32 v94, v95, v94
	v_fmac_f32_e32 v91, v90, v90
	v_add_f32_e32 v90, v91, v94
	v_mul_f32_e32 v91, v93, v93
	v_fmac_f32_e32 v91, v92, v92
	v_pk_add_f32 v[86:87], v[86:87], v[150:151]
	v_add_f32_e32 v94, v91, v90
	v_pk_add_f32 v[90:91], v[82:83], v[142:143]
	v_mul_f32_e32 v82, v87, v87
	v_mul_f32_e32 v83, v89, v89
	v_fmac_f32_e32 v82, v86, v86
	v_fmac_f32_e32 v83, v88, v88
	v_add_f32_e32 v82, v82, v83
	v_mul_f32_e32 v83, v91, v91
	v_cvt_pk_bf16_f32 v157, v92, v93
	v_pk_add_f32 v[92:93], v[84:85], v[144:145]
	v_fmac_f32_e32 v83, v90, v90
	v_add_f32_e32 v82, v83, v82
	v_mul_f32_e32 v83, v93, v93
	v_fmac_f32_e32 v83, v92, v92
	v_add_f32_e32 v82, v83, v82
	v_add_f32_e32 v82, v94, v82
	v_mov_b32_e32 v83, v82
	s_nop 1
	v_permlane16_swap_b32 v83, v82
	v_lshlrev_b64 v[172:173], 11, v[206:207]
	v_lshl_add_u64 v[172:173], s[22:23], 0, v[172:173]
	v_lshl_add_u64 v[172:173], v[198:199], 1, v[172:173]
	global_store_dwordx4 v[172:173], v[154:157], off
	global_store_dwordx4 v[170:171], v[86:89], off offset:512
	global_store_dwordx4 v[170:171], v[90:93], off offset:528
	s_waitcnt lgkmcnt(0)
	v_add_f32_e32 v82, v82, v83
	v_mov_b32_e32 v83, v82
	s_nop 1
	v_permlane32_swap_b32 v83, v82
	v_cvt_pk_bf16_f32 v84, v86, v87
	v_cvt_pk_bf16_f32 v85, v88, v89
	v_cvt_pk_bf16_f32 v86, v90, v91
	v_cvt_pk_bf16_f32 v87, v92, v93
	global_store_dwordx4 v[172:173], v[84:87], off offset:256
	s_and_saveexec_b64 s[34:35], s[4:5]
	s_cbranch_execz .LBB0_3998
	v_lshlrev_b64 v[84:85], 6, v[206:207]
	v_lshl_add_u64 v[84:85], s[10:11], 0, v[84:85]
	v_lshl_add_u64 v[84:85], s[30:31], 2, v[84:85]
	s_lshl_b32 s58, s44, 2
	s_mov_b32 s59, s68
	v_lshl_add_u64 v[84:85], v[84:85], 0, s[58:59]
	s_waitcnt lgkmcnt(0)
	v_add_f32_e32 v82, v82, v83
	global_store_dword v[84:85], v82, off
; __device__ __forceinline__ unsigned cvt_pk_bf16(float lo, float hi) { unsigned r; asm volatile("v_cvt_pk_bf16_f32 %0, %1, %2" : "=v"(r) : "v"(lo), "v"(hi)); return r; }
;     __device__ __forceinline__ void operator()(const f32x4 (&acc)[2][2][4][2], const Unit& u, int wr, int wc, int fr, int fq) const {
;     ...
;             if (g < 3) RESID_LOAD((g + 1) & 1, g + 1);
; #pragma unroll
;             for (int rr = 0; rr < 2; ++rr) {
;                 const int idx = 2 * g + rr, ai = idx >> 2, m = idx & 3;
;                 const int row = row0 + ai * HALF + m * 16;
;                 float* xr = X + (size_t)row * 1024 + col0; bf16_t* br = XB + (size_t)row * 1024 + col0;
;                 float ss = 0.f;
; #pragma unroll
;                 for (int bj = 0; bj < 2; ++bj) {
;                     f32x4* p = (f32x4*)(xr + bj * HALF);
;                     const f32x4 o0 = xv[g & 1][rr][bj][0] + acc[ai][bj][m][0] * scale, o1 = xv[g & 1][rr][bj][1] + acc[ai][bj][m][1] * scale;
;                     p[0] = o0; p[1] = o1;
;                     u32x4 w; w.x = cvt_pk_bf16(o0[0], o0[1]); w.y = cvt_pk_bf16(o0[2], o0[3]); w.z = cvt_pk_bf16(o1[0], o1[1]); w.w = cvt_pk_bf16(o1[2], o1[3]);
;                     *(u32x4*)(br + bj * HALF) = w;
;                     ss += (o0[0] * o0[0] + o0[1] * o0[1]) + (o0[2] * o0[2] + o0[3] * o0[3]) + (o1[0] * o1[0] + o1[1] * o1[1]) + (o1[2] * o1[2] + o1[3] * o1[3]);
;                 }
;                 ss += __shfl_xor(ss, 16); ss += __shfl_xor(ss, 32);
;                 if (fq == 0) ssq[(size_t)row * 16 + u.pn * 4 + wc] = ss;
;             }
.LBB0_3998:
	s_or_b64 exec, exec, s[34:35]
	s_waitcnt lgkmcnt(0)
	v_lshl_add_u64 v[82:83], s[8:9], 0, v[208:209]
	v_lshl_add_u64 v[86:87], v[198:199], 2, v[82:83]
	v_lshlrev_b64 v[82:83], 11, v[204:205]
	v_lshl_add_u64 v[82:83], s[22:23], 0, v[82:83]
	v_pk_add_f32 v[80:81], v[80:81], v[148:149]
	v_pk_add_f32 v[78:79], v[78:79], v[146:147]
	v_lshl_add_u64 v[88:89], v[198:199], 1, v[82:83]
	v_pk_add_f32 v[76:77], v[76:77], v[140:141]
	v_pk_add_f32 v[74:75], v[74:75], v[138:139]
	global_store_dwordx4 v[86:87], v[78:81], off
	global_store_dwordx4 v[86:87], v[74:77], off offset:16
	v_cvt_pk_bf16_f32 v82, v78, v79
	v_cvt_pk_bf16_f32 v83, v80, v81
	v_cvt_pk_bf16_f32 v84, v74, v75
	v_pk_add_f32 v[72:73], v[72:73], v[136:137]
	v_mul_f32_e32 v79, v79, v79
	v_fmac_f32_e32 v79, v78, v78
	v_mul_f32_e32 v78, v81, v81
	v_fmac_f32_e32 v78, v80, v80
	v_mul_f32_e32 v75, v75, v75
	v_add_f32_e32 v78, v79, v78
	v_fmac_f32_e32 v75, v74, v74
	v_add_f32_e32 v74, v75, v78
	v_mul_f32_e32 v75, v77, v77
	v_fmac_f32_e32 v75, v76, v76
	v_pk_add_f32 v[70:71], v[70:71], v[134:135]
	v_add_f32_e32 v78, v75, v74
	v_pk_add_f32 v[74:75], v[66:67], v[130:131]
	v_mul_f32_e32 v66, v71, v71
	v_mul_f32_e32 v67, v73, v73
	v_fmac_f32_e32 v66, v70, v70
	v_fmac_f32_e32 v67, v72, v72
	v_add_f32_e32 v66, v66, v67
	v_mul_f32_e32 v67, v75, v75
	v_cvt_pk_bf16_f32 v85, v76, v77
	v_pk_add_f32 v[76:77], v[68:69], v[132:133]
	v_fmac_f32_e32 v67, v74, v74
	v_add_f32_e32 v66, v67, v66
	v_mul_f32_e32 v67, v77, v77
	v_fmac_f32_e32 v67, v76, v76
	v_add_f32_e32 v66, v67, v66
	v_add_f32_e32 v66, v78, v66
	v_mov_b32_e32 v67, v66
	s_nop 1
	v_permlane16_swap_b32 v67, v66
	global_store_dwordx4 v[88:89], v[82:85], off
	global_store_dwordx4 v[86:87], v[70:73], off offset:512
	global_store_dwordx4 v[86:87], v[74:77], off offset:528
	v_cvt_pk_bf16_f32 v68, v70, v71
	v_cvt_pk_bf16_f32 v69, v72, v73
	s_waitcnt lgkmcnt(0)
	v_add_f32_e32 v66, v66, v67
	v_mov_b32_e32 v67, v66
	s_nop 1
	v_permlane32_swap_b32 v67, v66
	v_cvt_pk_bf16_f32 v70, v74, v75
	v_cvt_pk_bf16_f32 v71, v76, v77
	global_store_dwordx4 v[88:89], v[68:71], off offset:256
	s_and_saveexec_b64 s[34:35], s[4:5]
	s_cbranch_execz .LBB0_4000
	v_lshlrev_b64 v[68:69], 6, v[204:205]
	v_lshl_add_u64 v[68:69], s[10:11], 0, v[68:69]
	v_lshl_add_u64 v[68:69], s[30:31], 2, v[68:69]
	s_lshl_b32 s58, s44, 2
	s_mov_b32 s59, s68
	v_lshl_add_u64 v[68:69], v[68:69], 0, s[58:59]
	s_waitcnt lgkmcnt(0)
	v_add_f32_e32 v66, v66, v67
	global_store_dword v[68:69], v66, off
.LBB0_4000:
	s_or_b64 exec, exec, s[34:35]
	v_add_u32_e32 v134, 0xa0, v200
	v_add_u32_e32 v130, 0xb0, v200
	v_ashrrev_i32_e32 v135, 31, v134
	v_ashrrev_i32_e32 v131, 31, v130
	v_lshlrev_b64 v[136:137], 12, v[134:135]
	v_lshlrev_b64 v[132:133], 12, v[130:131]
	s_waitcnt lgkmcnt(0)
	v_lshl_add_u64 v[66:67], v[202:203], 0, v[136:137]
	v_lshl_add_u64 v[70:71], v[202:203], 0, v[132:133]
	global_load_dwordx4 v[90:93], v[66:67], off offset:16
	global_load_dwordx4 v[94:97], v[66:67], off
	global_load_dwordx4 v[82:85], v[66:67], off offset:528
	global_load_dwordx4 v[86:89], v[66:67], off offset:512
	global_load_dwordx4 v[74:77], v[70:71], off offset:16
	global_load_dwordx4 v[78:81], v[70:71], off
	s_nop 0
	global_load_dwordx4 v[66:69], v[70:71], off offset:528
	s_nop 0
	global_load_dwordx4 v[70:73], v[70:71], off offset:512
	v_lshl_add_u64 v[138:139], s[8:9], 0, v[168:169]
	v_lshl_add_u64 v[138:139], v[198:199], 2, v[138:139]
	s_waitcnt vmcnt(26)
	v_pk_add_f32 v[64:65], v[64:65], v[128:129]
	v_pk_add_f32 v[62:63], v[62:63], v[126:127]
	v_pk_add_f32 v[60:61], v[60:61], v[124:125]
	v_pk_add_f32 v[58:59], v[58:59], v[122:123]
	global_store_dwordx4 v[138:139], v[62:65], off
	global_store_dwordx4 v[138:139], v[58:61], off offset:16
	v_cvt_pk_bf16_f32 v122, v62, v63
	v_cvt_pk_bf16_f32 v123, v64, v65
	v_cvt_pk_bf16_f32 v124, v58, v59
	s_waitcnt vmcnt(26)
	v_pk_add_f32 v[56:57], v[56:57], v[120:121]
	v_mul_f32_e32 v63, v63, v63
	v_fmac_f32_e32 v63, v62, v62
	v_mul_f32_e32 v62, v65, v65
	v_fmac_f32_e32 v62, v64, v64
	v_mul_f32_e32 v59, v59, v59
	v_add_f32_e32 v62, v63, v62
	v_fmac_f32_e32 v59, v58, v58
	v_add_f32_e32 v58, v59, v62
	v_mul_f32_e32 v59, v61, v61
	v_fmac_f32_e32 v59, v60, v60
	v_pk_add_f32 v[54:55], v[54:55], v[118:119]
	v_add_f32_e32 v62, v59, v58
	v_pk_add_f32 v[58:59], v[50:51], v[114:115]
	v_mul_f32_e32 v50, v55, v55
	v_mul_f32_e32 v51, v57, v57
	v_fmac_f32_e32 v50, v54, v54
	v_fmac_f32_e32 v51, v56, v56
	v_add_f32_e32 v50, v50, v51
	v_mul_f32_e32 v51, v59, v59
	v_cvt_pk_bf16_f32 v125, v60, v61
	v_pk_add_f32 v[60:61], v[52:53], v[116:117]
	v_fmac_f32_e32 v51, v58, v58
	v_add_f32_e32 v50, v51, v50
	v_mul_f32_e32 v51, v61, v61
	v_fmac_f32_e32 v51, v60, v60
	v_add_f32_e32 v50, v51, v50
	v_add_f32_e32 v50, v62, v50
	v_mov_b32_e32 v51, v50
	s_nop 1
	v_permlane16_swap_b32 v51, v50
	v_lshlrev_b64 v[140:141], 11, v[166:167]
	v_lshl_add_u64 v[140:141], s[22:23], 0, v[140:141]
	v_lshl_add_u64 v[140:141], v[198:199], 1, v[140:141]
	global_store_dwordx4 v[140:141], v[122:125], off
	global_store_dwordx4 v[138:139], v[54:57], off offset:512
	global_store_dwordx4 v[138:139], v[58:61], off offset:528
	s_waitcnt lgkmcnt(0)
	v_add_f32_e32 v50, v50, v51
	v_mov_b32_e32 v51, v50
	s_nop 1
	v_permlane32_swap_b32 v51, v50
	v_cvt_pk_bf16_f32 v52, v54, v55
	v_cvt_pk_bf16_f32 v53, v56, v57
	v_cvt_pk_bf16_f32 v54, v58, v59
	v_cvt_pk_bf16_f32 v55, v60, v61
	global_store_dwordx4 v[140:141], v[52:55], off offset:256
	s_and_saveexec_b64 s[34:35], s[4:5]
	s_cbranch_execz .LBB0_4002
	v_lshlrev_b64 v[52:53], 6, v[166:167]
	v_lshl_add_u64 v[52:53], s[10:11], 0, v[52:53]
	v_lshl_add_u64 v[52:53], s[30:31], 2, v[52:53]
	s_lshl_b32 s58, s44, 2
	s_mov_b32 s59, s68
	v_lshl_add_u64 v[52:53], v[52:53], 0, s[58:59]
	s_waitcnt lgkmcnt(0)
	v_add_f32_e32 v50, v50, v51
	global_store_dword v[52:53], v50, off
; __device__ __forceinline__ unsigned cvt_pk_bf16(float lo, float hi) { unsigned r; asm volatile("v_cvt_pk_bf16_f32 %0, %1, %2" : "=v"(r) : "v"(lo), "v"(hi)); return r; }
;     __device__ __forceinline__ void operator()(const f32x4 (&acc)[2][2][4][2], const Unit& u, int wr, int wc, int fr, int fq) const {
;     ...
;             for (int rr = 0; rr < 2; ++rr) {
;                 const int idx = 2 * g + rr, ai = idx >> 2, m = idx & 3;
;                 const int row = row0 + ai * HALF + m * 16;
;                 float* xr = X + (size_t)row * 1024 + col0; bf16_t* br = XB + (size_t)row * 1024 + col0;
;                 float ss = 0.f;
; #pragma unroll
;                 for (int bj = 0; bj < 2; ++bj) {
;                     f32x4* p = (f32x4*)(xr + bj * HALF);
;                     const f32x4 o0 = xv[g & 1][rr][bj][0] + acc[ai][bj][m][0] * scale, o1 = xv[g & 1][rr][bj][1] + acc[ai][bj][m][1] * scale;
;                     p[0] = o0; p[1] = o1;
;                     u32x4 w; w.x = cvt_pk_bf16(o0[0], o0[1]); w.y = cvt_pk_bf16(o0[2], o0[3]); w.z = cvt_pk_bf16(o1[0], o1[1]); w.w = cvt_pk_bf16(o1[2], o1[3]);
;                     *(u32x4*)(br + bj * HALF) = w;
;                     ss += (o0[0] * o0[0] + o0[1] * o0[1]) + (o0[2] * o0[2] + o0[3] * o0[3]) + (o1[0] * o1[0] + o1[1] * o1[1]) + (o1[2] * o1[2] + o1[3] * o1[3]);
;                 }
;                 ss += __shfl_xor(ss, 16); ss += __shfl_xor(ss, 32);
;                 if (fq == 0) ssq[(size_t)row * 16 + u.pn * 4 + wc] = ss;
;             }
.LBB0_4002:
	s_or_b64 exec, exec, s[34:35]
	s_waitcnt lgkmcnt(0)
	v_lshl_add_u64 v[50:51], s[8:9], 0, v[164:165]
	v_lshl_add_u64 v[54:55], v[198:199], 2, v[50:51]
	v_lshlrev_b64 v[50:51], 11, v[162:163]
	v_lshl_add_u64 v[50:51], s[22:23], 0, v[50:51]
	s_waitcnt vmcnt(28)
	v_pk_add_f32 v[48:49], v[48:49], v[112:113]
	v_pk_add_f32 v[46:47], v[46:47], v[110:111]
	v_lshl_add_u64 v[56:57], v[198:199], 1, v[50:51]
	v_pk_add_f32 v[44:45], v[44:45], v[108:109]
	v_pk_add_f32 v[42:43], v[42:43], v[106:107]
	global_store_dwordx4 v[54:55], v[46:49], off
	global_store_dwordx4 v[54:55], v[42:45], off offset:16
	v_cvt_pk_bf16_f32 v50, v46, v47
	v_cvt_pk_bf16_f32 v51, v48, v49
	v_cvt_pk_bf16_f32 v52, v42, v43
	s_waitcnt vmcnt(28)
	v_pk_add_f32 v[40:41], v[40:41], v[104:105]
	v_mul_f32_e32 v47, v47, v47
	v_fmac_f32_e32 v47, v46, v46
	v_mul_f32_e32 v46, v49, v49
	v_fmac_f32_e32 v46, v48, v48
	v_mul_f32_e32 v43, v43, v43
	v_add_f32_e32 v46, v47, v46
	v_fmac_f32_e32 v43, v42, v42
	v_add_f32_e32 v42, v43, v46
	v_mul_f32_e32 v43, v45, v45
	v_fmac_f32_e32 v43, v44, v44
	v_pk_add_f32 v[38:39], v[38:39], v[102:103]
	v_add_f32_e32 v46, v43, v42
	v_pk_add_f32 v[42:43], v[34:35], v[98:99]
	v_mul_f32_e32 v34, v39, v39
	v_mul_f32_e32 v35, v41, v41
	v_fmac_f32_e32 v34, v38, v38
	v_fmac_f32_e32 v35, v40, v40
	v_add_f32_e32 v34, v34, v35
	v_mul_f32_e32 v35, v43, v43
	v_cvt_pk_bf16_f32 v53, v44, v45
	v_pk_add_f32 v[44:45], v[36:37], v[100:101]
	v_fmac_f32_e32 v35, v42, v42
	v_add_f32_e32 v34, v35, v34
	v_mul_f32_e32 v35, v45, v45
	v_fmac_f32_e32 v35, v44, v44
	v_add_f32_e32 v34, v35, v34
	v_add_f32_e32 v34, v46, v34
	v_mov_b32_e32 v35, v34
	s_nop 1
	v_permlane16_swap_b32 v35, v34
	global_store_dwordx4 v[56:57], v[50:53], off
	global_store_dwordx4 v[54:55], v[38:41], off offset:512
	global_store_dwordx4 v[54:55], v[42:45], off offset:528
	v_cvt_pk_bf16_f32 v36, v38, v39
	v_cvt_pk_bf16_f32 v37, v40, v41
	s_waitcnt lgkmcnt(0)
	v_add_f32_e32 v34, v34, v35
	v_mov_b32_e32 v35, v34
	s_nop 1
	v_permlane32_swap_b32 v35, v34
	v_cvt_pk_bf16_f32 v38, v42, v43
	v_cvt_pk_bf16_f32 v39, v44, v45
	global_store_dwordx4 v[56:57], v[36:39], off offset:256
	s_and_saveexec_b64 s[34:35], s[4:5]
	s_cbranch_execz .LBB0_4004
	v_lshlrev_b64 v[36:37], 6, v[162:163]
	v_lshl_add_u64 v[36:37], s[10:11], 0, v[36:37]
	v_lshl_add_u64 v[36:37], s[30:31], 2, v[36:37]
	s_lshl_b32 s58, s44, 2
	s_mov_b32 s59, s68
	v_lshl_add_u64 v[36:37], v[36:37], 0, s[58:59]
	s_waitcnt lgkmcnt(0)
	v_add_f32_e32 v34, v34, v35
	global_store_dword v[36:37], v34, off
; __device__ __forceinline__ unsigned cvt_pk_bf16(float lo, float hi) { unsigned r; asm volatile("v_cvt_pk_bf16_f32 %0, %1, %2" : "=v"(r) : "v"(lo), "v"(hi)); return r; }
;     __device__ __forceinline__ void operator()(const f32x4 (&acc)[2][2][4][2], const Unit& u, int wr, int wc, int fr, int fq) const {
;     ...
;             for (int rr = 0; rr < 2; ++rr) {
;                 const int idx = 2 * g + rr, ai = idx >> 2, m = idx & 3;
;                 const int row = row0 + ai * HALF + m * 16;
;                 float* xr = X + (size_t)row * 1024 + col0; bf16_t* br = XB + (size_t)row * 1024 + col0;
;                 float ss = 0.f;
; #pragma unroll
;                 for (int bj = 0; bj < 2; ++bj) {
;                     f32x4* p = (f32x4*)(xr + bj * HALF);
;                     const f32x4 o0 = xv[g & 1][rr][bj][0] + acc[ai][bj][m][0] * scale, o1 = xv[g & 1][rr][bj][1] + acc[ai][bj][m][1] * scale;
;                     p[0] = o0; p[1] = o1;
;                     u32x4 w; w.x = cvt_pk_bf16(o0[0], o0[1]); w.y = cvt_pk_bf16(o0[2], o0[3]); w.z = cvt_pk_bf16(o1[0], o1[1]); w.w = cvt_pk_bf16(o1[2], o1[3]);
;                     *(u32x4*)(br + bj * HALF) = w;
;                     ss += (o0[0] * o0[0] + o0[1] * o0[1]) + (o0[2] * o0[2] + o0[3] * o0[3]) + (o1[0] * o1[0] + o1[1] * o1[1]) + (o1[2] * o1[2] + o1[3] * o1[3]);
;                 }
;                 ss += __shfl_xor(ss, 16); ss += __shfl_xor(ss, 32);
;                 if (fq == 0) ssq[(size_t)row * 16 + u.pn * 4 + wc] = ss;
;             }
.LBB0_4004:
	s_or_b64 exec, exec, s[34:35]
	s_waitcnt lgkmcnt(0)
	v_lshl_add_u64 v[34:35], s[8:9], 0, v[136:137]
	v_lshl_add_u64 v[38:39], v[198:199], 2, v[34:35]
	v_lshlrev_b64 v[34:35], 11, v[134:135]
	v_lshl_add_u64 v[34:35], s[22:23], 0, v[34:35]
	s_waitcnt vmcnt(18)
	v_pk_add_f32 v[32:33], v[32:33], v[96:97]
	v_pk_add_f32 v[30:31], v[30:31], v[94:95]
	v_lshl_add_u64 v[40:41], v[198:199], 1, v[34:35]
	v_pk_add_f32 v[28:29], v[28:29], v[92:93]
	v_pk_add_f32 v[26:27], v[26:27], v[90:91]
	global_store_dwordx4 v[38:39], v[30:33], off
	global_store_dwordx4 v[38:39], v[26:29], off offset:16
	v_cvt_pk_bf16_f32 v34, v30, v31
	v_cvt_pk_bf16_f32 v35, v32, v33
	v_cvt_pk_bf16_f32 v36, v26, v27
	s_waitcnt vmcnt(18)
	v_pk_add_f32 v[24:25], v[24:25], v[88:89]
	v_mul_f32_e32 v31, v31, v31
	v_fmac_f32_e32 v31, v30, v30
	v_mul_f32_e32 v30, v33, v33
	v_fmac_f32_e32 v30, v32, v32
	v_mul_f32_e32 v27, v27, v27
	v_add_f32_e32 v30, v31, v30
	v_fmac_f32_e32 v27, v26, v26
	v_add_f32_e32 v26, v27, v30
	v_mul_f32_e32 v27, v29, v29
	v_fmac_f32_e32 v27, v28, v28
	v_pk_add_f32 v[22:23], v[22:23], v[86:87]
	v_add_f32_e32 v30, v27, v26
	v_pk_add_f32 v[26:27], v[18:19], v[82:83]
	v_mul_f32_e32 v18, v23, v23
	v_mul_f32_e32 v19, v25, v25
	v_fmac_f32_e32 v18, v22, v22
	v_fmac_f32_e32 v19, v24, v24
	v_add_f32_e32 v18, v18, v19
	v_mul_f32_e32 v19, v27, v27
	v_cvt_pk_bf16_f32 v37, v28, v29
	v_pk_add_f32 v[28:29], v[20:21], v[84:85]
	v_fmac_f32_e32 v19, v26, v26
	v_add_f32_e32 v18, v19, v18
	v_mul_f32_e32 v19, v29, v29
	v_fmac_f32_e32 v19, v28, v28
	v_add_f32_e32 v18, v19, v18
	v_add_f32_e32 v18, v30, v18
	v_mov_b32_e32 v19, v18
	s_nop 1
	v_permlane16_swap_b32 v19, v18
	global_store_dwordx4 v[40:41], v[34:37], off
	global_store_dwordx4 v[38:39], v[22:25], off offset:512
	global_store_dwordx4 v[38:39], v[26:29], off offset:528
	v_cvt_pk_bf16_f32 v20, v22, v23
	v_cvt_pk_bf16_f32 v21, v24, v25
	s_waitcnt lgkmcnt(0)
	v_add_f32_e32 v18, v18, v19
	v_mov_b32_e32 v19, v18
	s_nop 1
	v_permlane32_swap_b32 v19, v18
	v_cvt_pk_bf16_f32 v22, v26, v27
	v_cvt_pk_bf16_f32 v23, v28, v29
	global_store_dwordx4 v[40:41], v[20:23], off offset:256
	s_and_saveexec_b64 s[34:35], s[4:5]
	s_cbranch_execz .LBB0_4006
	v_lshlrev_b64 v[20:21], 6, v[134:135]
	v_lshl_add_u64 v[20:21], s[10:11], 0, v[20:21]
	v_lshl_add_u64 v[20:21], s[30:31], 2, v[20:21]
	s_lshl_b32 s58, s44, 2
	s_mov_b32 s59, s68
	v_lshl_add_u64 v[20:21], v[20:21], 0, s[58:59]
	s_waitcnt lgkmcnt(0)
	v_add_f32_e32 v18, v18, v19
	global_store_dword v[20:21], v18, off
.LBB0_4006:
	s_or_b64 exec, exec, s[34:35]
	s_waitcnt lgkmcnt(0)
	v_lshl_add_u64 v[18:19], s[8:9], 0, v[132:133]
	v_lshl_add_u64 v[22:23], v[198:199], 2, v[18:19]
	v_lshlrev_b64 v[18:19], 11, v[130:131]
	v_lshl_add_u64 v[18:19], s[22:23], 0, v[18:19]
	s_waitcnt vmcnt(20)
	v_pk_add_f32 v[16:17], v[16:17], v[80:81]
	v_pk_add_f32 v[14:15], v[14:15], v[78:79]
	v_lshl_add_u64 v[24:25], v[198:199], 1, v[18:19]
	v_pk_add_f32 v[12:13], v[12:13], v[76:77]
	v_pk_add_f32 v[10:11], v[10:11], v[74:75]
	global_store_dwordx4 v[22:23], v[14:17], off
	global_store_dwordx4 v[22:23], v[10:13], off offset:16
	v_cvt_pk_bf16_f32 v18, v14, v15
	v_cvt_pk_bf16_f32 v19, v16, v17
	v_cvt_pk_bf16_f32 v20, v10, v11
	s_waitcnt vmcnt(20)
	v_pk_add_f32 v[8:9], v[8:9], v[72:73]
	v_mul_f32_e32 v15, v15, v15
	v_fmac_f32_e32 v15, v14, v14
	v_mul_f32_e32 v14, v17, v17
	v_fmac_f32_e32 v14, v16, v16
	v_mul_f32_e32 v11, v11, v11
	v_add_f32_e32 v14, v15, v14
	v_fmac_f32_e32 v11, v10, v10
	v_add_f32_e32 v10, v11, v14
	v_mul_f32_e32 v11, v13, v13
	v_fmac_f32_e32 v11, v12, v12
	v_pk_add_f32 v[6:7], v[6:7], v[70:71]
	v_add_f32_e32 v14, v11, v10
	v_pk_add_f32 v[10:11], v[2:3], v[66:67]
	v_mul_f32_e32 v2, v7, v7
	v_mul_f32_e32 v3, v9, v9
	v_fmac_f32_e32 v2, v6, v6
	v_fmac_f32_e32 v3, v8, v8
	v_add_f32_e32 v2, v2, v3
	v_mul_f32_e32 v3, v11, v11
	v_cvt_pk_bf16_f32 v21, v12, v13
	v_pk_add_f32 v[12:13], v[4:5], v[68:69]
	v_fmac_f32_e32 v3, v10, v10
	v_add_f32_e32 v2, v3, v2
	v_mul_f32_e32 v3, v13, v13
	v_fmac_f32_e32 v3, v12, v12
	v_add_f32_e32 v2, v3, v2
	v_add_f32_e32 v2, v14, v2
	v_mov_b32_e32 v3, v2
	s_nop 1
	v_permlane16_swap_b32 v3, v2
	global_store_dwordx4 v[24:25], v[18:21], off
	global_store_dwordx4 v[22:23], v[6:9], off offset:512
	global_store_dwordx4 v[22:23], v[10:13], off offset:528
	v_cvt_pk_bf16_f32 v4, v6, v7
	v_cvt_pk_bf16_f32 v5, v8, v9
	s_waitcnt lgkmcnt(0)
	v_add_f32_e32 v2, v2, v3
	v_mov_b32_e32 v3, v2
	s_nop 1
	v_permlane32_swap_b32 v3, v2
	v_cvt_pk_bf16_f32 v6, v10, v11
	v_cvt_pk_bf16_f32 v7, v12, v13
	global_store_dwordx4 v[24:25], v[4:7], off offset:256
	s_and_saveexec_b64 s[34:35], s[4:5]
	s_cbranch_execz .LBB0_4008
	v_lshlrev_b64 v[4:5], 6, v[130:131]
	v_lshl_add_u64 v[4:5], s[10:11], 0, v[4:5]
	v_lshl_add_u64 v[4:5], s[30:31], 2, v[4:5]
	s_lshl_b32 s30, s44, 2
	s_mov_b32 s31, s68
	v_lshl_add_u64 v[4:5], v[4:5], 0, s[30:31]
	s_waitcnt lgkmcnt(0)
	v_add_f32_e32 v2, v2, v3
	global_store_dword v[4:5], v2, off

; __device__ __forceinline__ unsigned cvt_pk_bf16(float lo, float hi) { unsigned r; asm volatile("v_cvt_pk_bf16_f32 %0, %1, %2" : "=v"(r) : "v"(lo), "v"(hi)); return r; }
;     __device__ __forceinline__ void operator()(const f32x4 (&acc)[2][2][4][2], const Unit& u, int wr, int wc, int fr, int fq) const {
;         const int row0 = u.pm * BM + wr * 64 + fr, col0 = u.pn * BM + wc * 32 + 8 * fq;
;         f32x4 xv[2][2][2][2];
;     ...
;         RESID_LOAD(0, 0);
; #pragma unroll
;         for (int g = 0; g < 4; ++g) {
;             if (g < 3) RESID_LOAD((g + 1) & 1, g + 1);
; #pragma unroll
;             for (int rr = 0; rr < 2; ++rr) {
;                 const int idx = 2 * g + rr, ai = idx >> 2, m = idx & 3;
;                 const int row = row0 + ai * HALF + m * 16;
;                 float* xr = X + (size_t)row * 1024 + col0; bf16_t* br = XB + (size_t)row * 1024 + col0;
;                 float ss = 0.f;
; #pragma unroll
;                 for (int bj = 0; bj < 2; ++bj) {
;                     f32x4* p = (f32x4*)(xr + bj * HALF);
;                     const f32x4 o0 = xv[g & 1][rr][bj][0] + acc[ai][bj][m][0] * scale, o1 = xv[g & 1][rr][bj][1] + acc[ai][bj][m][1] * scale;
;                     p[0] = o0; p[1] = o1;
;                     u32x4 w; w.x = cvt_pk_bf16(o0[0], o0[1]); w.y = cvt_pk_bf16(o0[2], o0[3]); w.z = cvt_pk_bf16(o1[0], o1[1]); w.w = cvt_pk_bf16(o1[2], o1[3]);
;                     *(u32x4*)(br + bj * HALF) = w;
;                     ss += (o0[0] * o0[0] + o0[1] * o0[1]) + (o0[2] * o0[2] + o0[3] * o0[3]) + (o1[0] * o1[0] + o1[1] * o1[1]) + (o1[2] * o1[2] + o1[3] * o1[3]);
;                 }
;                 ss += __shfl_xor(ss, 16); ss += __shfl_xor(ss, 32);
;                 if (fq == 0) ssq[(size_t)row * 16 + u.pn * 4 + wc] = ss;
;             }
.LBB0_4932:
	v_lshl_or_b32 v142, s57, 8, v243
	v_lshl_add_u32 v192, s58, 8, v1
	v_ashrrev_i32_e32 v143, 31, v142
	v_lshlrev_b64 v[228:229], 2, v[142:143]
	v_ashrrev_i32_e32 v193, 31, v192
	v_lshl_add_u64 v[194:195], s[8:9], 0, v[228:229]
	v_lshlrev_b64 v[250:251], 12, v[192:193]
	v_lshl_add_u64 v[2:3], v[194:195], 0, v[250:251]
	global_load_dwordx4 v[62:65], v[2:3], off offset:16
	global_load_dwordx4 v[246:249], v[2:3], off
	global_load_dwordx4 v[50:53], v[2:3], off offset:528
	global_load_dwordx4 v[54:57], v[2:3], off offset:512
	v_or_b32_e32 v58, 16, v192
	v_ashrrev_i32_e32 v59, 31, v58
	v_or_b32_e32 v214, 32, v192
	v_or_b32_e32 v204, 48, v192
	v_lshlrev_b64 v[60:61], 12, v[58:59]
	v_ashrrev_i32_e32 v215, 31, v214
	v_ashrrev_i32_e32 v205, 31, v204
	v_lshl_add_u64 v[2:3], v[194:195], 0, v[60:61]
	v_lshlrev_b64 v[218:219], 12, v[214:215]
	v_lshlrev_b64 v[216:217], 12, v[204:205]
	global_load_dwordx4 v[42:45], v[2:3], off offset:16
	global_load_dwordx4 v[46:49], v[2:3], off
	global_load_dwordx4 v[34:37], v[2:3], off offset:528
	global_load_dwordx4 v[38:41], v[2:3], off offset:512
	v_lshl_add_u64 v[2:3], v[194:195], 0, v[218:219]
	v_lshl_add_u64 v[6:7], v[194:195], 0, v[216:217]
	global_load_dwordx4 v[26:29], v[2:3], off offset:16
	global_load_dwordx4 v[30:33], v[2:3], off
	global_load_dwordx4 v[14:17], v[2:3], off offset:528
	global_load_dwordx4 v[22:25], v[2:3], off offset:512
	global_load_dwordx4 v[10:13], v[6:7], off offset:16
	global_load_dwordx4 v[18:21], v[6:7], off
	s_nop 0
	global_load_dwordx4 v[2:5], v[6:7], off offset:528
	s_nop 0
	global_load_dwordx4 v[6:9], v[6:7], off offset:512
	v_lshl_add_u64 v[250:251], s[8:9], 0, v[250:251]
	v_lshl_add_u64 v[228:229], v[250:251], 0, v[228:229]
	v_lshlrev_b64 v[250:251], 11, v[192:193]
	v_lshl_add_u64 v[250:251], s[22:23], 0, v[250:251]
	v_lshl_add_u64 v[250:251], v[142:143], 1, v[250:251]
	s_lshl_b32 s30, s57, 2
	s_ashr_i32 s31, s30, 31
	s_waitcnt vmcnt(0)
	v_pk_add_f32 v[64:65], v[210:211], v[64:65]
	v_pk_add_f32 v[248:249], v[206:207], v[248:249]
	v_pk_add_f32 v[246:247], v[212:213], v[246:247]
	v_pk_add_f32 v[62:63], v[208:209], v[62:63]
	global_store_dwordx4 v[228:229], v[246:249], off
	global_store_dwordx4 v[228:229], v[62:65], off offset:16
	v_cvt_pk_bf16_f32 v206, v246, v247
	v_cvt_pk_bf16_f32 v207, v248, v249
	v_cvt_pk_bf16_f32 v208, v62, v63
	v_cvt_pk_bf16_f32 v209, v64, v65
	global_store_dwordx4 v[250:251], v[206:209], off
	s_nop 0
	v_mul_f32_e32 v63, v63, v63
	v_fmac_f32_e32 v63, v62, v62
	v_mul_f32_e32 v206, v247, v247
	v_mul_f32_e32 v207, v249, v249
	v_fmac_f32_e32 v206, v246, v246
	v_fmac_f32_e32 v207, v248, v248
	v_add_f32_e32 v206, v206, v207
	v_add_f32_e32 v62, v63, v206
	v_mul_f32_e32 v63, v65, v65
	v_fmac_f32_e32 v63, v64, v64
	v_pk_add_f32 v[56:57], v[202:203], v[56:57]
	v_pk_add_f32 v[54:55], v[200:201], v[54:55]
	v_add_f32_e32 v206, v63, v62
	v_pk_add_f32 v[52:53], v[198:199], v[52:53]
	v_pk_add_f32 v[50:51], v[196:197], v[50:51]
	global_store_dwordx4 v[228:229], v[54:57], off offset:512
	global_store_dwordx4 v[228:229], v[50:53], off offset:528
	v_cvt_pk_bf16_f32 v62, v54, v55
	v_cvt_pk_bf16_f32 v63, v56, v57
	v_cvt_pk_bf16_f32 v64, v50, v51
	v_cvt_pk_bf16_f32 v65, v52, v53
	s_nop 0
	v_mul_f32_e32 v55, v55, v55
	v_fmac_f32_e32 v55, v54, v54
	v_mul_f32_e32 v54, v57, v57
	v_fmac_f32_e32 v54, v56, v56
	v_mul_f32_e32 v51, v51, v51
	v_add_f32_e32 v54, v55, v54
	v_fmac_f32_e32 v51, v50, v50
	v_add_f32_e32 v50, v51, v54
	v_mul_f32_e32 v51, v53, v53
	v_fmac_f32_e32 v51, v52, v52
	v_add_f32_e32 v50, v51, v50
	v_add_f32_e32 v50, v206, v50
	v_mov_b32_e32 v51, v50
	s_nop 1
	v_permlane16_swap_b32 v51, v50
	global_store_dwordx4 v[250:251], v[62:65], off offset:256
	s_waitcnt lgkmcnt(0)
	v_add_f32_e32 v50, v50, v51
	v_mov_b32_e32 v51, v50
	s_nop 1
	v_permlane32_swap_b32 v51, v50
	s_and_saveexec_b64 s[34:35], s[4:5]
	s_cbranch_execz .LBB0_4934
	v_lshlrev_b64 v[52:53], 6, v[192:193]
	v_lshl_add_u64 v[52:53], s[10:11], 0, v[52:53]
	v_lshl_add_u64 v[52:53], s[30:31], 2, v[52:53]
	s_lshl_b32 s58, s44, 2
	s_mov_b32 s59, s68
	v_lshl_add_u64 v[52:53], v[52:53], 0, s[58:59]
	s_waitcnt lgkmcnt(0)
	v_add_f32_e32 v50, v50, v51
	global_store_dword v[52:53], v50, off
.LBB0_4934:
	s_or_b64 exec, exec, s[34:35]
	s_waitcnt lgkmcnt(0)
	v_lshl_add_u64 v[50:51], s[8:9], 0, v[60:61]
	v_lshl_add_u64 v[54:55], v[142:143], 2, v[50:51]
	v_lshlrev_b64 v[50:51], 11, v[58:59]
	v_lshl_add_u64 v[50:51], s[22:23], 0, v[50:51]
	v_pk_add_f32 v[48:49], v[190:191], v[48:49]
	v_pk_add_f32 v[46:47], v[188:189], v[46:47]
	v_lshl_add_u64 v[56:57], v[142:143], 1, v[50:51]
	v_pk_add_f32 v[44:45], v[186:187], v[44:45]
	v_pk_add_f32 v[42:43], v[184:185], v[42:43]
	global_store_dwordx4 v[54:55], v[46:49], off
	global_store_dwordx4 v[54:55], v[42:45], off offset:16
	v_cvt_pk_bf16_f32 v50, v46, v47
	v_cvt_pk_bf16_f32 v51, v48, v49
	v_cvt_pk_bf16_f32 v52, v42, v43
	v_pk_add_f32 v[40:41], v[182:183], v[40:41]
	v_mul_f32_e32 v47, v47, v47
	v_fmac_f32_e32 v47, v46, v46
	v_mul_f32_e32 v46, v49, v49
	v_fmac_f32_e32 v46, v48, v48
	v_mul_f32_e32 v43, v43, v43
	v_add_f32_e32 v46, v47, v46
	v_fmac_f32_e32 v43, v42, v42
	v_add_f32_e32 v42, v43, v46
	v_mul_f32_e32 v43, v45, v45
	v_fmac_f32_e32 v43, v44, v44
	v_pk_add_f32 v[38:39], v[180:181], v[38:39]
	v_add_f32_e32 v46, v43, v42
	v_pk_add_f32 v[42:43], v[176:177], v[34:35]
	v_mul_f32_e32 v34, v39, v39
	v_mul_f32_e32 v35, v41, v41
	v_fmac_f32_e32 v34, v38, v38
	v_fmac_f32_e32 v35, v40, v40
	v_add_f32_e32 v34, v34, v35
	v_mul_f32_e32 v35, v43, v43
	v_cvt_pk_bf16_f32 v53, v44, v45
	v_pk_add_f32 v[44:45], v[178:179], v[36:37]
	v_fmac_f32_e32 v35, v42, v42
	v_add_f32_e32 v34, v35, v34
	v_mul_f32_e32 v35, v45, v45
	v_fmac_f32_e32 v35, v44, v44
	v_add_f32_e32 v34, v35, v34
	v_add_f32_e32 v34, v46, v34
	v_mov_b32_e32 v35, v34
	s_nop 1
	v_permlane16_swap_b32 v35, v34
	global_store_dwordx4 v[56:57], v[50:53], off
	global_store_dwordx4 v[54:55], v[38:41], off offset:512
	global_store_dwordx4 v[54:55], v[42:45], off offset:528
	v_cvt_pk_bf16_f32 v36, v38, v39
	v_cvt_pk_bf16_f32 v37, v40, v41
	s_waitcnt lgkmcnt(0)
	v_add_f32_e32 v34, v34, v35
	v_mov_b32_e32 v35, v34
	s_nop 1
	v_permlane32_swap_b32 v35, v34
	v_cvt_pk_bf16_f32 v38, v42, v43
	v_cvt_pk_bf16_f32 v39, v44, v45
	global_store_dwordx4 v[56:57], v[36:39], off offset:256
	s_and_saveexec_b64 s[34:35], s[4:5]
	s_cbranch_execz .LBB0_4936
	v_lshlrev_b64 v[36:37], 6, v[58:59]
	v_lshl_add_u64 v[36:37], s[10:11], 0, v[36:37]
	v_lshl_add_u64 v[36:37], s[30:31], 2, v[36:37]
	s_lshl_b32 s58, s44, 2
	s_mov_b32 s59, s68
	v_lshl_add_u64 v[36:37], v[36:37], 0, s[58:59]
	s_waitcnt lgkmcnt(0)
	v_add_f32_e32 v34, v34, v35
	global_store_dword v[36:37], v34, off
; __device__ __forceinline__ unsigned cvt_pk_bf16(float lo, float hi) { unsigned r; asm volatile("v_cvt_pk_bf16_f32 %0, %1, %2" : "=v"(r) : "v"(lo), "v"(hi)); return r; }
;     __device__ __forceinline__ void operator()(const f32x4 (&acc)[2][2][4][2], const Unit& u, int wr, int wc, int fr, int fq) const {
;     ...
;             if (g < 3) RESID_LOAD((g + 1) & 1, g + 1);
; #pragma unroll
;             for (int rr = 0; rr < 2; ++rr) {
;                 const int idx = 2 * g + rr, ai = idx >> 2, m = idx & 3;
;                 const int row = row0 + ai * HALF + m * 16;
;                 float* xr = X + (size_t)row * 1024 + col0; bf16_t* br = XB + (size_t)row * 1024 + col0;
;                 float ss = 0.f;
; #pragma unroll
;                 for (int bj = 0; bj < 2; ++bj) {
;                     f32x4* p = (f32x4*)(xr + bj * HALF);
;                     const f32x4 o0 = xv[g & 1][rr][bj][0] + acc[ai][bj][m][0] * scale, o1 = xv[g & 1][rr][bj][1] + acc[ai][bj][m][1] * scale;
;                     p[0] = o0; p[1] = o1;
;                     u32x4 w; w.x = cvt_pk_bf16(o0[0], o0[1]); w.y = cvt_pk_bf16(o0[2], o0[3]); w.z = cvt_pk_bf16(o1[0], o1[1]); w.w = cvt_pk_bf16(o1[2], o1[3]);
;                     *(u32x4*)(br + bj * HALF) = w;
;                     ss += (o0[0] * o0[0] + o0[1] * o0[1]) + (o0[2] * o0[2] + o0[3] * o0[3]) + (o1[0] * o1[0] + o1[1] * o1[1]) + (o1[2] * o1[2] + o1[3] * o1[3]);
;                 }
;                 ss += __shfl_xor(ss, 16); ss += __shfl_xor(ss, 32);
;                 if (fq == 0) ssq[(size_t)row * 16 + u.pn * 4 + wc] = ss;
;             }
.LBB0_4936:
	s_or_b64 exec, exec, s[34:35]
	v_add_u32_e32 v180, 0x80, v192
	v_add_u32_e32 v176, 0x90, v192
	v_ashrrev_i32_e32 v181, 31, v180
	v_ashrrev_i32_e32 v177, 31, v176
	v_lshlrev_b64 v[182:183], 12, v[180:181]
	v_lshlrev_b64 v[178:179], 12, v[176:177]
	s_waitcnt lgkmcnt(0)
	v_lshl_add_u64 v[34:35], v[194:195], 0, v[182:183]
	v_lshl_add_u64 v[38:39], v[194:195], 0, v[178:179]
	global_load_dwordx4 v[58:61], v[34:35], off offset:16
	global_load_dwordx4 v[62:65], v[34:35], off
	global_load_dwordx4 v[50:53], v[34:35], off offset:528
	global_load_dwordx4 v[54:57], v[34:35], off offset:512
	global_load_dwordx4 v[42:45], v[38:39], off offset:16
	global_load_dwordx4 v[46:49], v[38:39], off
	s_nop 0
	global_load_dwordx4 v[34:37], v[38:39], off offset:528
	s_nop 0
	global_load_dwordx4 v[38:41], v[38:39], off offset:512
	v_lshl_add_u64 v[184:185], s[8:9], 0, v[218:219]
	v_lshl_add_u64 v[184:185], v[142:143], 2, v[184:185]
	v_pk_add_f32 v[32:33], v[174:175], v[32:33]
	v_pk_add_f32 v[30:31], v[172:173], v[30:31]
	v_pk_add_f32 v[28:29], v[170:171], v[28:29]
	v_pk_add_f32 v[26:27], v[168:169], v[26:27]
	global_store_dwordx4 v[184:185], v[30:33], off
	global_store_dwordx4 v[184:185], v[26:29], off offset:16
	v_cvt_pk_bf16_f32 v168, v30, v31
	v_cvt_pk_bf16_f32 v169, v32, v33
	v_cvt_pk_bf16_f32 v170, v26, v27
	v_pk_add_f32 v[24:25], v[166:167], v[24:25]
	v_mul_f32_e32 v31, v31, v31
	v_fmac_f32_e32 v31, v30, v30
	v_mul_f32_e32 v30, v33, v33
	v_fmac_f32_e32 v30, v32, v32
	v_mul_f32_e32 v27, v27, v27
	v_add_f32_e32 v30, v31, v30
	v_fmac_f32_e32 v27, v26, v26
	v_add_f32_e32 v26, v27, v30
	v_mul_f32_e32 v27, v29, v29
	v_fmac_f32_e32 v27, v28, v28
	v_pk_add_f32 v[22:23], v[164:165], v[22:23]
	v_add_f32_e32 v30, v27, v26
	v_pk_add_f32 v[26:27], v[160:161], v[14:15]
	v_mul_f32_e32 v14, v23, v23
	v_mul_f32_e32 v15, v25, v25
	v_fmac_f32_e32 v14, v22, v22
	v_fmac_f32_e32 v15, v24, v24
	v_add_f32_e32 v14, v14, v15
	v_mul_f32_e32 v15, v27, v27
	v_cvt_pk_bf16_f32 v171, v28, v29
	v_pk_add_f32 v[28:29], v[162:163], v[16:17]
	v_fmac_f32_e32 v15, v26, v26
	v_add_f32_e32 v14, v15, v14
	v_mul_f32_e32 v15, v29, v29
	v_fmac_f32_e32 v15, v28, v28
	v_add_f32_e32 v14, v15, v14
	v_add_f32_e32 v14, v30, v14
	v_mov_b32_e32 v15, v14
	s_nop 1
	v_permlane16_swap_b32 v15, v14
	v_lshlrev_b64 v[186:187], 11, v[214:215]
	v_lshl_add_u64 v[186:187], s[22:23], 0, v[186:187]
	v_lshl_add_u64 v[186:187], v[142:143], 1, v[186:187]
	global_store_dwordx4 v[186:187], v[168:171], off
	global_store_dwordx4 v[184:185], v[22:25], off offset:512
	global_store_dwordx4 v[184:185], v[26:29], off offset:528
	s_waitcnt lgkmcnt(0)
	v_add_f32_e32 v14, v14, v15
	v_mov_b32_e32 v15, v14
	s_nop 1
	v_permlane32_swap_b32 v15, v14
	v_cvt_pk_bf16_f32 v22, v22, v23
	v_cvt_pk_bf16_f32 v23, v24, v25
	v_cvt_pk_bf16_f32 v24, v26, v27
	v_cvt_pk_bf16_f32 v25, v28, v29
	global_store_dwordx4 v[186:187], v[22:25], off offset:256
	s_and_saveexec_b64 s[34:35], s[4:5]
	s_cbranch_execz .LBB0_4938
	v_lshlrev_b64 v[16:17], 6, v[214:215]
	v_lshl_add_u64 v[16:17], s[10:11], 0, v[16:17]
	v_lshl_add_u64 v[16:17], s[30:31], 2, v[16:17]
	s_lshl_b32 s58, s44, 2
	s_mov_b32 s59, s68
	v_lshl_add_u64 v[16:17], v[16:17], 0, s[58:59]
	s_waitcnt lgkmcnt(0)
	v_add_f32_e32 v14, v14, v15
	global_store_dword v[16:17], v14, off
.LBB0_4938:
	s_or_b64 exec, exec, s[34:35]
	s_waitcnt lgkmcnt(0)
	v_lshl_add_u64 v[14:15], s[8:9], 0, v[216:217]
	v_lshl_add_u64 v[22:23], v[142:143], 2, v[14:15]
	v_lshlrev_b64 v[14:15], 11, v[204:205]
	v_lshl_add_u64 v[14:15], s[22:23], 0, v[14:15]
	v_lshl_add_u64 v[24:25], v[142:143], 1, v[14:15]
	v_pk_add_f32 v[16:17], v[158:159], v[20:21]
	v_pk_add_f32 v[14:15], v[156:157], v[18:19]
	v_pk_add_f32 v[12:13], v[154:155], v[12:13]
	v_pk_add_f32 v[10:11], v[152:153], v[10:11]
	global_store_dwordx4 v[22:23], v[14:17], off
	global_store_dwordx4 v[22:23], v[10:13], off offset:16
	v_cvt_pk_bf16_f32 v18, v14, v15
	v_cvt_pk_bf16_f32 v19, v16, v17
	v_cvt_pk_bf16_f32 v20, v10, v11
	v_pk_add_f32 v[8:9], v[150:151], v[8:9]
	v_mul_f32_e32 v15, v15, v15
	v_fmac_f32_e32 v15, v14, v14
	v_mul_f32_e32 v14, v17, v17
	v_fmac_f32_e32 v14, v16, v16
	v_mul_f32_e32 v11, v11, v11
	v_add_f32_e32 v14, v15, v14
	v_fmac_f32_e32 v11, v10, v10
	v_add_f32_e32 v10, v11, v14
	v_mul_f32_e32 v11, v13, v13
	v_fmac_f32_e32 v11, v12, v12
	v_pk_add_f32 v[6:7], v[148:149], v[6:7]
	v_add_f32_e32 v14, v11, v10
	v_pk_add_f32 v[10:11], v[144:145], v[2:3]
	v_mul_f32_e32 v2, v7, v7
	v_mul_f32_e32 v3, v9, v9
	v_fmac_f32_e32 v2, v6, v6
	v_fmac_f32_e32 v3, v8, v8
	v_add_f32_e32 v2, v2, v3
	v_mul_f32_e32 v3, v11, v11
	v_cvt_pk_bf16_f32 v21, v12, v13
	v_pk_add_f32 v[12:13], v[146:147], v[4:5]
	v_fmac_f32_e32 v3, v10, v10
	v_add_f32_e32 v2, v3, v2
	v_mul_f32_e32 v3, v13, v13
	v_fmac_f32_e32 v3, v12, v12
	v_add_f32_e32 v2, v3, v2
	v_add_f32_e32 v2, v14, v2
	v_mov_b32_e32 v3, v2
	s_nop 1
	v_permlane16_swap_b32 v3, v2
	global_store_dwordx4 v[24:25], v[18:21], off
	global_store_dwordx4 v[22:23], v[6:9], off offset:512
	global_store_dwordx4 v[22:23], v[10:13], off offset:528
	v_cvt_pk_bf16_f32 v4, v6, v7
	v_cvt_pk_bf16_f32 v5, v8, v9
	s_waitcnt lgkmcnt(0)
	v_add_f32_e32 v2, v2, v3
	v_mov_b32_e32 v3, v2
	s_nop 1
	v_permlane32_swap_b32 v3, v2
	v_cvt_pk_bf16_f32 v6, v10, v11
	v_cvt_pk_bf16_f32 v7, v12, v13
	global_store_dwordx4 v[24:25], v[4:7], off offset:256
	s_and_saveexec_b64 s[34:35], s[4:5]
	s_cbranch_execz .LBB0_4940
	v_lshlrev_b64 v[4:5], 6, v[204:205]
	v_lshl_add_u64 v[4:5], s[10:11], 0, v[4:5]
	v_lshl_add_u64 v[4:5], s[30:31], 2, v[4:5]
	s_lshl_b32 s58, s44, 2
	s_mov_b32 s59, s68
	v_lshl_add_u64 v[4:5], v[4:5], 0, s[58:59]
	s_waitcnt lgkmcnt(0)
	v_add_f32_e32 v2, v2, v3
	global_store_dword v[4:5], v2, off
; __device__ __forceinline__ unsigned cvt_pk_bf16(float lo, float hi) { unsigned r; asm volatile("v_cvt_pk_bf16_f32 %0, %1, %2" : "=v"(r) : "v"(lo), "v"(hi)); return r; }
;     __device__ __forceinline__ void operator()(const f32x4 (&acc)[2][2][4][2], const Unit& u, int wr, int wc, int fr, int fq) const {
;     ...
;             if (g < 3) RESID_LOAD((g + 1) & 1, g + 1);
; #pragma unroll
;             for (int rr = 0; rr < 2; ++rr) {
;                 const int idx = 2 * g + rr, ai = idx >> 2, m = idx & 3;
;                 const int row = row0 + ai * HALF + m * 16;
;                 float* xr = X + (size_t)row * 1024 + col0; bf16_t* br = XB + (size_t)row * 1024 + col0;
;                 float ss = 0.f;
; #pragma unroll
;                 for (int bj = 0; bj < 2; ++bj) {
;                     f32x4* p = (f32x4*)(xr + bj * HALF);
;                     const f32x4 o0 = xv[g & 1][rr][bj][0] + acc[ai][bj][m][0] * scale, o1 = xv[g & 1][rr][bj][1] + acc[ai][bj][m][1] * scale;
;                     p[0] = o0; p[1] = o1;
;                     u32x4 w; w.x = cvt_pk_bf16(o0[0], o0[1]); w.y = cvt_pk_bf16(o0[2], o0[3]); w.z = cvt_pk_bf16(o1[0], o1[1]); w.w = cvt_pk_bf16(o1[2], o1[3]);
;                     *(u32x4*)(br + bj * HALF) = w;
;                     ss += (o0[0] * o0[0] + o0[1] * o0[1]) + (o0[2] * o0[2] + o0[3] * o0[3]) + (o1[0] * o1[0] + o1[1] * o1[1]) + (o1[2] * o1[2] + o1[3] * o1[3]);
;                 }
;                 ss += __shfl_xor(ss, 16); ss += __shfl_xor(ss, 32);
;                 if (fq == 0) ssq[(size_t)row * 16 + u.pn * 4 + wc] = ss;
;             }
.LBB0_4940:
	s_or_b64 exec, exec, s[34:35]
	v_add_u32_e32 v148, 0xa0, v192
	v_add_u32_e32 v144, 0xb0, v192
	v_ashrrev_i32_e32 v149, 31, v148
	v_ashrrev_i32_e32 v145, 31, v144
	v_lshlrev_b64 v[150:151], 12, v[148:149]
	v_lshlrev_b64 v[146:147], 12, v[144:145]
	s_waitcnt lgkmcnt(0)
	v_lshl_add_u64 v[2:3], v[194:195], 0, v[150:151]
	v_lshl_add_u64 v[6:7], v[194:195], 0, v[146:147]
	global_load_dwordx4 v[26:29], v[2:3], off offset:16
	global_load_dwordx4 v[30:33], v[2:3], off
	global_load_dwordx4 v[18:21], v[2:3], off offset:528
	global_load_dwordx4 v[22:25], v[2:3], off offset:512
	global_load_dwordx4 v[10:13], v[6:7], off offset:16
	global_load_dwordx4 v[14:17], v[6:7], off
	s_nop 0
	global_load_dwordx4 v[2:5], v[6:7], off offset:528
	s_nop 0
	global_load_dwordx4 v[6:9], v[6:7], off offset:512
	v_lshl_add_u64 v[152:153], s[8:9], 0, v[182:183]
	v_lshl_add_u64 v[152:153], v[142:143], 2, v[152:153]
	s_waitcnt vmcnt(26)
	v_pk_add_f32 v[64:65], v[128:129], v[64:65]
	v_pk_add_f32 v[62:63], v[126:127], v[62:63]
	v_pk_add_f32 v[60:61], v[124:125], v[60:61]
	v_pk_add_f32 v[58:59], v[122:123], v[58:59]
	global_store_dwordx4 v[152:153], v[62:65], off
	global_store_dwordx4 v[152:153], v[58:61], off offset:16
	v_cvt_pk_bf16_f32 v122, v62, v63
	v_cvt_pk_bf16_f32 v123, v64, v65
	v_cvt_pk_bf16_f32 v124, v58, v59
	s_waitcnt vmcnt(26)
	v_pk_add_f32 v[56:57], v[120:121], v[56:57]
	v_mul_f32_e32 v63, v63, v63
	v_fmac_f32_e32 v63, v62, v62
	v_mul_f32_e32 v62, v65, v65
	v_fmac_f32_e32 v62, v64, v64
	v_mul_f32_e32 v59, v59, v59
	v_add_f32_e32 v62, v63, v62
	v_fmac_f32_e32 v59, v58, v58
	v_add_f32_e32 v58, v59, v62
	v_mul_f32_e32 v59, v61, v61
	v_fmac_f32_e32 v59, v60, v60
	v_pk_add_f32 v[54:55], v[118:119], v[54:55]
	v_add_f32_e32 v62, v59, v58
	v_pk_add_f32 v[58:59], v[114:115], v[50:51]
	v_mul_f32_e32 v50, v55, v55
	v_mul_f32_e32 v51, v57, v57
	v_fmac_f32_e32 v50, v54, v54
	v_fmac_f32_e32 v51, v56, v56
	v_add_f32_e32 v50, v50, v51
	v_mul_f32_e32 v51, v59, v59
	v_cvt_pk_bf16_f32 v125, v60, v61
	v_pk_add_f32 v[60:61], v[116:117], v[52:53]
	v_fmac_f32_e32 v51, v58, v58
	v_add_f32_e32 v50, v51, v50
	v_mul_f32_e32 v51, v61, v61
	v_fmac_f32_e32 v51, v60, v60
	v_add_f32_e32 v50, v51, v50
	v_add_f32_e32 v50, v62, v50
	v_mov_b32_e32 v51, v50
	s_nop 1
	v_permlane16_swap_b32 v51, v50
	v_lshlrev_b64 v[154:155], 11, v[180:181]
	v_lshl_add_u64 v[154:155], s[22:23], 0, v[154:155]
	v_lshl_add_u64 v[154:155], v[142:143], 1, v[154:155]
	global_store_dwordx4 v[154:155], v[122:125], off
	global_store_dwordx4 v[152:153], v[54:57], off offset:512
	global_store_dwordx4 v[152:153], v[58:61], off offset:528
	s_waitcnt lgkmcnt(0)
	v_add_f32_e32 v50, v50, v51
	v_mov_b32_e32 v51, v50
	s_nop 1
	v_permlane32_swap_b32 v51, v50
	v_cvt_pk_bf16_f32 v52, v54, v55
	v_cvt_pk_bf16_f32 v53, v56, v57
	v_cvt_pk_bf16_f32 v54, v58, v59
	v_cvt_pk_bf16_f32 v55, v60, v61
	global_store_dwordx4 v[154:155], v[52:55], off offset:256
	s_and_saveexec_b64 s[34:35], s[4:5]
	s_cbranch_execz .LBB0_4942
	v_lshlrev_b64 v[52:53], 6, v[180:181]
	v_lshl_add_u64 v[52:53], s[10:11], 0, v[52:53]
	v_lshl_add_u64 v[52:53], s[30:31], 2, v[52:53]
	s_lshl_b32 s58, s44, 2
	s_mov_b32 s59, s68
	v_lshl_add_u64 v[52:53], v[52:53], 0, s[58:59]
	s_waitcnt lgkmcnt(0)
	v_add_f32_e32 v50, v50, v51
	global_store_dword v[52:53], v50, off
.LBB0_4942:
	s_or_b64 exec, exec, s[34:35]
	s_waitcnt lgkmcnt(0)
	v_lshl_add_u64 v[50:51], s[8:9], 0, v[178:179]
	v_lshl_add_u64 v[54:55], v[142:143], 2, v[50:51]
	v_lshlrev_b64 v[50:51], 11, v[176:177]
	v_lshl_add_u64 v[50:51], s[22:23], 0, v[50:51]
	s_waitcnt vmcnt(28)
	v_pk_add_f32 v[48:49], v[112:113], v[48:49]
	v_pk_add_f32 v[46:47], v[110:111], v[46:47]
	v_lshl_add_u64 v[56:57], v[142:143], 1, v[50:51]
	v_pk_add_f32 v[44:45], v[108:109], v[44:45]
	v_pk_add_f32 v[42:43], v[106:107], v[42:43]
	global_store_dwordx4 v[54:55], v[46:49], off
	global_store_dwordx4 v[54:55], v[42:45], off offset:16
	v_cvt_pk_bf16_f32 v50, v46, v47
	v_cvt_pk_bf16_f32 v51, v48, v49
	v_cvt_pk_bf16_f32 v52, v42, v43
	s_waitcnt vmcnt(28)
	v_pk_add_f32 v[40:41], v[104:105], v[40:41]
	v_mul_f32_e32 v47, v47, v47
	v_fmac_f32_e32 v47, v46, v46
	v_mul_f32_e32 v46, v49, v49
	v_fmac_f32_e32 v46, v48, v48
	v_mul_f32_e32 v43, v43, v43
	v_add_f32_e32 v46, v47, v46
	v_fmac_f32_e32 v43, v42, v42
	v_add_f32_e32 v42, v43, v46
	v_mul_f32_e32 v43, v45, v45
	v_fmac_f32_e32 v43, v44, v44
	v_pk_add_f32 v[38:39], v[102:103], v[38:39]
	v_add_f32_e32 v46, v43, v42
	v_pk_add_f32 v[42:43], v[98:99], v[34:35]
	v_mul_f32_e32 v34, v39, v39
	v_mul_f32_e32 v35, v41, v41
	v_fmac_f32_e32 v34, v38, v38
	v_fmac_f32_e32 v35, v40, v40
	v_add_f32_e32 v34, v34, v35
	v_mul_f32_e32 v35, v43, v43
	v_cvt_pk_bf16_f32 v53, v44, v45
	v_pk_add_f32 v[44:45], v[100:101], v[36:37]
	v_fmac_f32_e32 v35, v42, v42
	v_add_f32_e32 v34, v35, v34
	v_mul_f32_e32 v35, v45, v45
	v_fmac_f32_e32 v35, v44, v44
	v_add_f32_e32 v34, v35, v34
	v_add_f32_e32 v34, v46, v34
	v_mov_b32_e32 v35, v34
	s_nop 1
	v_permlane16_swap_b32 v35, v34
	global_store_dwordx4 v[56:57], v[50:53], off
	global_store_dwordx4 v[54:55], v[38:41], off offset:512
	global_store_dwordx4 v[54:55], v[42:45], off offset:528
	v_cvt_pk_bf16_f32 v36, v38, v39
	v_cvt_pk_bf16_f32 v37, v40, v41
	s_waitcnt lgkmcnt(0)
	v_add_f32_e32 v34, v34, v35
	v_mov_b32_e32 v35, v34
	s_nop 1
	v_permlane32_swap_b32 v35, v34
	v_cvt_pk_bf16_f32 v38, v42, v43
	v_cvt_pk_bf16_f32 v39, v44, v45
	global_store_dwordx4 v[56:57], v[36:39], off offset:256
	s_and_saveexec_b64 s[34:35], s[4:5]
	s_cbranch_execz .LBB0_4944
	v_lshlrev_b64 v[36:37], 6, v[176:177]
	v_lshl_add_u64 v[36:37], s[10:11], 0, v[36:37]
	v_lshl_add_u64 v[36:37], s[30:31], 2, v[36:37]
	s_lshl_b32 s58, s44, 2
	s_mov_b32 s59, s68
	v_lshl_add_u64 v[36:37], v[36:37], 0, s[58:59]
	s_waitcnt lgkmcnt(0)
	v_add_f32_e32 v34, v34, v35
	global_store_dword v[36:37], v34, off
; __device__ __forceinline__ unsigned cvt_pk_bf16(float lo, float hi) { unsigned r; asm volatile("v_cvt_pk_bf16_f32 %0, %1, %2" : "=v"(r) : "v"(lo), "v"(hi)); return r; }
;     __device__ __forceinline__ void operator()(const f32x4 (&acc)[2][2][4][2], const Unit& u, int wr, int wc, int fr, int fq) const {
;     ...
;             for (int rr = 0; rr < 2; ++rr) {
;                 const int idx = 2 * g + rr, ai = idx >> 2, m = idx & 3;
;                 const int row = row0 + ai * HALF + m * 16;
;                 float* xr = X + (size_t)row * 1024 + col0; bf16_t* br = XB + (size_t)row * 1024 + col0;
;                 float ss = 0.f;
; #pragma unroll
;                 for (int bj = 0; bj < 2; ++bj) {
;                     f32x4* p = (f32x4*)(xr + bj * HALF);
;                     const f32x4 o0 = xv[g & 1][rr][bj][0] + acc[ai][bj][m][0] * scale, o1 = xv[g & 1][rr][bj][1] + acc[ai][bj][m][1] * scale;
;                     p[0] = o0; p[1] = o1;
;                     u32x4 w; w.x = cvt_pk_bf16(o0[0], o0[1]); w.y = cvt_pk_bf16(o0[2], o0[3]); w.z = cvt_pk_bf16(o1[0], o1[1]); w.w = cvt_pk_bf16(o1[2], o1[3]);
;                     *(u32x4*)(br + bj * HALF) = w;
;                     ss += (o0[0] * o0[0] + o0[1] * o0[1]) + (o0[2] * o0[2] + o0[3] * o0[3]) + (o1[0] * o1[0] + o1[1] * o1[1]) + (o1[2] * o1[2] + o1[3] * o1[3]);
;                 }
;                 ss += __shfl_xor(ss, 16); ss += __shfl_xor(ss, 32);
;                 if (fq == 0) ssq[(size_t)row * 16 + u.pn * 4 + wc] = ss;
;             }
.LBB0_4944:
	s_or_b64 exec, exec, s[34:35]
	s_waitcnt lgkmcnt(0)
	v_lshl_add_u64 v[34:35], s[8:9], 0, v[150:151]
	v_lshl_add_u64 v[38:39], v[142:143], 2, v[34:35]
	v_lshlrev_b64 v[34:35], 11, v[148:149]
	v_lshl_add_u64 v[34:35], s[22:23], 0, v[34:35]
	s_waitcnt vmcnt(18)
	v_pk_add_f32 v[32:33], v[96:97], v[32:33]
	v_pk_add_f32 v[30:31], v[94:95], v[30:31]
	v_lshl_add_u64 v[40:41], v[142:143], 1, v[34:35]
	v_pk_add_f32 v[28:29], v[92:93], v[28:29]
	v_pk_add_f32 v[26:27], v[90:91], v[26:27]
	global_store_dwordx4 v[38:39], v[30:33], off
	global_store_dwordx4 v[38:39], v[26:29], off offset:16
	v_cvt_pk_bf16_f32 v34, v30, v31
	v_cvt_pk_bf16_f32 v35, v32, v33
	v_cvt_pk_bf16_f32 v36, v26, v27
	s_waitcnt vmcnt(18)
	v_pk_add_f32 v[24:25], v[88:89], v[24:25]
	v_mul_f32_e32 v31, v31, v31
	v_fmac_f32_e32 v31, v30, v30
	v_mul_f32_e32 v30, v33, v33
	v_fmac_f32_e32 v30, v32, v32
	v_mul_f32_e32 v27, v27, v27
	v_add_f32_e32 v30, v31, v30
	v_fmac_f32_e32 v27, v26, v26
	v_add_f32_e32 v26, v27, v30
	v_mul_f32_e32 v27, v29, v29
	v_fmac_f32_e32 v27, v28, v28
	v_pk_add_f32 v[22:23], v[86:87], v[22:23]
	v_add_f32_e32 v30, v27, v26
	v_pk_add_f32 v[26:27], v[82:83], v[18:19]
	v_mul_f32_e32 v18, v23, v23
	v_mul_f32_e32 v19, v25, v25
	v_fmac_f32_e32 v18, v22, v22
	v_fmac_f32_e32 v19, v24, v24
	v_add_f32_e32 v18, v18, v19
	v_mul_f32_e32 v19, v27, v27
	v_cvt_pk_bf16_f32 v37, v28, v29
	v_pk_add_f32 v[28:29], v[84:85], v[20:21]
	v_fmac_f32_e32 v19, v26, v26
	v_add_f32_e32 v18, v19, v18
	v_mul_f32_e32 v19, v29, v29
	v_fmac_f32_e32 v19, v28, v28
	v_add_f32_e32 v18, v19, v18
	v_add_f32_e32 v18, v30, v18
	v_mov_b32_e32 v19, v18
	s_nop 1
	v_permlane16_swap_b32 v19, v18
	global_store_dwordx4 v[40:41], v[34:37], off
	global_store_dwordx4 v[38:39], v[22:25], off offset:512
	global_store_dwordx4 v[38:39], v[26:29], off offset:528
	v_cvt_pk_bf16_f32 v20, v22, v23
	v_cvt_pk_bf16_f32 v21, v24, v25
	s_waitcnt lgkmcnt(0)
	v_add_f32_e32 v18, v18, v19
	v_mov_b32_e32 v19, v18
	s_nop 1
	v_permlane32_swap_b32 v19, v18
	v_cvt_pk_bf16_f32 v22, v26, v27
	v_cvt_pk_bf16_f32 v23, v28, v29
	global_store_dwordx4 v[40:41], v[20:23], off offset:256
	s_and_saveexec_b64 s[34:35], s[4:5]
	s_cbranch_execz .LBB0_4946
	v_lshlrev_b64 v[20:21], 6, v[148:149]
	v_lshl_add_u64 v[20:21], s[10:11], 0, v[20:21]
	v_lshl_add_u64 v[20:21], s[30:31], 2, v[20:21]
	s_lshl_b32 s58, s44, 2
	s_mov_b32 s59, s68
	v_lshl_add_u64 v[20:21], v[20:21], 0, s[58:59]
	s_waitcnt lgkmcnt(0)
	v_add_f32_e32 v18, v18, v19
	global_store_dword v[20:21], v18, off
.LBB0_4946:
	s_or_b64 exec, exec, s[34:35]
	s_waitcnt lgkmcnt(0)
	v_lshl_add_u64 v[18:19], s[8:9], 0, v[146:147]
	v_lshl_add_u64 v[22:23], v[142:143], 2, v[18:19]
	v_lshlrev_b64 v[18:19], 11, v[144:145]
	v_lshl_add_u64 v[18:19], s[22:23], 0, v[18:19]
	s_waitcnt vmcnt(20)
	v_pk_add_f32 v[16:17], v[80:81], v[16:17]
	v_pk_add_f32 v[14:15], v[78:79], v[14:15]
	v_lshl_add_u64 v[24:25], v[142:143], 1, v[18:19]
	v_pk_add_f32 v[12:13], v[76:77], v[12:13]
	v_pk_add_f32 v[10:11], v[74:75], v[10:11]
	global_store_dwordx4 v[22:23], v[14:17], off
	global_store_dwordx4 v[22:23], v[10:13], off offset:16
	v_cvt_pk_bf16_f32 v18, v14, v15
	v_cvt_pk_bf16_f32 v19, v16, v17
	v_cvt_pk_bf16_f32 v20, v10, v11
	s_waitcnt vmcnt(20)
	v_pk_add_f32 v[8:9], v[72:73], v[8:9]
	v_mul_f32_e32 v15, v15, v15
	v_fmac_f32_e32 v15, v14, v14
	v_mul_f32_e32 v14, v17, v17
	v_fmac_f32_e32 v14, v16, v16
	v_mul_f32_e32 v11, v11, v11
	v_add_f32_e32 v14, v15, v14
	v_fmac_f32_e32 v11, v10, v10
	v_add_f32_e32 v10, v11, v14
	v_mul_f32_e32 v11, v13, v13
	v_fmac_f32_e32 v11, v12, v12
	v_pk_add_f32 v[6:7], v[70:71], v[6:7]
	v_add_f32_e32 v14, v11, v10
	v_pk_add_f32 v[10:11], v[66:67], v[2:3]
	v_mul_f32_e32 v2, v7, v7
	v_mul_f32_e32 v3, v9, v9
	v_fmac_f32_e32 v2, v6, v6
	v_fmac_f32_e32 v3, v8, v8
	v_add_f32_e32 v2, v2, v3
	v_mul_f32_e32 v3, v11, v11
	v_cvt_pk_bf16_f32 v21, v12, v13
	v_pk_add_f32 v[12:13], v[68:69], v[4:5]
	v_fmac_f32_e32 v3, v10, v10
	v_add_f32_e32 v2, v3, v2
	v_mul_f32_e32 v3, v13, v13
	v_fmac_f32_e32 v3, v12, v12
	v_add_f32_e32 v2, v3, v2
	v_add_f32_e32 v2, v14, v2
	v_mov_b32_e32 v3, v2
	s_nop 1
	v_permlane16_swap_b32 v3, v2
	global_store_dwordx4 v[24:25], v[18:21], off
	global_store_dwordx4 v[22:23], v[6:9], off offset:512
	global_store_dwordx4 v[22:23], v[10:13], off offset:528
	v_cvt_pk_bf16_f32 v4, v6, v7
	v_cvt_pk_bf16_f32 v5, v8, v9
	s_waitcnt lgkmcnt(0)
	v_add_f32_e32 v2, v2, v3
	v_mov_b32_e32 v3, v2
	s_nop 1
	v_permlane32_swap_b32 v3, v2
	v_cvt_pk_bf16_f32 v6, v10, v11
	v_cvt_pk_bf16_f32 v7, v12, v13
	global_store_dwordx4 v[24:25], v[4:7], off offset:256
	s_and_saveexec_b64 s[34:35], s[4:5]
	s_cbranch_execz .LBB0_4948
	v_lshlrev_b64 v[4:5], 6, v[144:145]
	v_lshl_add_u64 v[4:5], s[10:11], 0, v[4:5]
	v_lshl_add_u64 v[4:5], s[30:31], 2, v[4:5]
	s_lshl_b32 s30, s44, 2
	s_mov_b32 s31, s68
	v_lshl_add_u64 v[4:5], v[4:5], 0, s[30:31]
	s_waitcnt lgkmcnt(0)
	v_add_f32_e32 v2, v2, v3
	global_store_dword v[4:5], v2, off
